# same B0 fragment-read placement applied to the out-projection and w_o GEMM K-loops
# speedup vs baseline: 1.0283x; 1.0008x over previous
; #define PG8_STAGE(bufoff, gbase, voff) do { _Pragma("unroll") for (int _i = 0; _i < 2; ++_i) \
;         __builtin_amdgcn_global_load_lds((const unsigned*)((const char*)(gbase) + (voff)[_i]), (LAS unsigned*)(lds + (bufoff) + ldsw + _i * 8192), 16, 0, 0); } while (0)
; #define PG8_LDA(dst, b, h) do { _Pragma("unroll") for (int m = 0; m < 4; ++m) _Pragma("unroll") for (int k = 0; k < 2; ++k) dst[m][k] = *(const LAS bf16x8*)(lds + PG8_SA(b, h) + aoff + m * 2048 + k * 1024); } while (0)
; #define PG8_LDB(dst, b, h) do { _Pragma("unroll") for (int n = 0; n < 2; ++n) _Pragma("unroll") for (int k = 0; k < 2; ++k) dst[n][k] = *(const LAS bf16x8*)(lds + PG8_SB(b, h) + boff + n * 2048 + k * 1024); } while (0)
; #define PG8_MMA(ai, bj, At, Bt) do { __builtin_amdgcn_s_setprio(1); _Pragma("unroll") for (int m = 0; m < 4; ++m) _Pragma("unroll") for (int n = 0; n < 2; ++n) _Pragma("unroll") for (int k = 0; k < 2; ++k) \
;         acc[ai][bj][m][n] = __builtin_amdgcn_mfma_f32_16x16x32_bf16(Bt[n][k], At[m][k], acc[ai][bj][m][n], 0, 0, 0); __builtin_amdgcn_s_setprio(0); } while (0)
; #define PG8_WAIT_L(n) asm volatile("s_waitcnt lgkmcnt(" #n ")" ::: "memory")
; #define PG8_BAR __builtin_amdgcn_s_barrier()
; #define PG8_SCHED __builtin_amdgcn_sched_barrier(0)
; template <class Epi, class Sched>
; __device__ __forceinline__ void gemm_phase(const int TID, LAS unsigned char* lds, const int lda, const int ldb, const Sched& S, const Epi& E) {
;     ...
;             PG8_LDB(B0, 0, 0); PG8_SCHED; PG8_LDA(At, 0, 0); PG8_STAGE(PG8_SA(1, 1), a1 + hA, voffA);
;             PG8_WAIT_L(8); PG8_BAR; PG8_WAIT_L(0); PG8_MMA(0, 0, At, B0); PG8_BAR; PG8_SCHED;
;             PG8_LDB(B1, 0, 1); PG8_STAGE(PG8_SB(0, 0), b2, voffB);
;             PG8_BAR; PG8_WAIT_L(0); PG8_MMA(0, 1, At, B1); PG8_BAR;
;             PG8_LDA(At, 0, 1); PG8_STAGE(PG8_SA(0, 0), a2, voffA);
;             PG8_BAR; PG8_WAIT_L(0); PG8_MMA(1, 0, At, B0); PG8_BAR; PG8_SCHED;
.LBB0_27:
	v_add_u32_e32 v158, 0x10000, v155
	ds_read_b128 v[140:143], v158
	ds_read_b128 v[144:147], v158 offset:1024
	ds_read_b128 v[148:151], v158 offset:2048
	ds_read_b128 v[158:161], v158 offset:3072
.Lk7_body:
	s_add_u32 s8, s50, 0xfff80080
	s_addc_u32 s9, s51, -1
	s_add_i32 s10, 0, 0x10000
	s_cmp_eq_u32 s49, 28
	s_cselect_b32 s55, s45, s9
	s_cselect_b32 s54, s44, s8
	s_cselect_b32 s53, s47, s43
	s_cselect_b32 s52, s46, s41
	v_lshl_add_u64 v[204:205], s[50:51], 0, v[138:139]
	s_add_i32 m0, s24, 0xc000
	ds_read_b128 v[162:165], v157
	ds_read_b128 v[166:169], v157 offset:1024
	ds_read_b128 v[170:173], v157 offset:2048
	ds_read_b128 v[174:177], v157 offset:3072
	ds_read_b128 v[178:181], v157 offset:4096
	ds_read_b128 v[186:189], v157 offset:5120
	ds_read_b128 v[196:199], v157 offset:6144
	ds_read_b128 v[200:203], v157 offset:7168
	global_load_lds_dwordx4 v[204:205], off
	v_lshl_add_u64 v[204:205], s[50:51], 0, v[136:137]
	s_add_i32 m0, s24, 0xe000
	s_nop 0
	global_load_lds_dwordx4 v[204:205], off
	s_waitcnt lgkmcnt(8)
	s_barrier
	s_waitcnt lgkmcnt(0)
	s_setprio 1
	s_waitcnt lgkmcnt(0)
	v_mfma_f32_16x16x32_bf16 v[130:133], v[140:143], v[162:165], v[130:133]
	v_mfma_f32_16x16x32_bf16 v[126:129], v[148:151], v[162:165], v[126:129]
	v_mfma_f32_16x16x32_bf16 v[114:117], v[140:143], v[170:173], v[114:117]
	v_mfma_f32_16x16x32_bf16 v[110:113], v[148:151], v[170:173], v[110:113]
	v_mfma_f32_16x16x32_bf16 v[98:101], v[140:143], v[178:181], v[98:101]
	v_mfma_f32_16x16x32_bf16 v[94:97], v[148:151], v[178:181], v[94:97]
	v_mfma_f32_16x16x32_bf16 v[82:85], v[140:143], v[196:199], v[82:85]
	v_mfma_f32_16x16x32_bf16 v[78:81], v[148:151], v[196:199], v[78:81]
	v_mfma_f32_16x16x32_bf16 v[130:133], v[144:147], v[166:169], v[130:133]
	v_mfma_f32_16x16x32_bf16 v[126:129], v[158:161], v[166:169], v[126:129]
	v_mfma_f32_16x16x32_bf16 v[114:117], v[144:147], v[174:177], v[114:117]
	v_mfma_f32_16x16x32_bf16 v[110:113], v[158:161], v[174:177], v[110:113]
	v_mfma_f32_16x16x32_bf16 v[98:101], v[144:147], v[186:189], v[98:101]
	v_mfma_f32_16x16x32_bf16 v[94:97], v[158:161], v[186:189], v[94:97]
	v_mfma_f32_16x16x32_bf16 v[82:85], v[144:147], v[200:203], v[82:85]
	v_mfma_f32_16x16x32_bf16 v[78:81], v[158:161], v[200:203], v[78:81]
	s_setprio 0
	s_barrier
	s_add_i32 s11, 0, 0x14000
	s_add_i32 s8, s10, s23
	v_add_u32_e32 v182, s11, v155
	v_lshl_add_u64 v[220:221], s[52:53], 0, v[12:13]
	s_mov_b32 m0, s8
	ds_read_b128 v[204:207], v182
	ds_read_b128 v[208:211], v182 offset:1024
	ds_read_b128 v[212:215], v182 offset:2048
	ds_read_b128 v[216:219], v182 offset:3072
	global_load_lds_dwordx4 v[220:221], off
	v_lshl_add_u64 v[222:223], s[52:53], 0, v[134:135]
	s_add_i32 m0, s8, 0x2000
	s_nop 0
	global_load_lds_dwordx4 v[222:223], off
	s_barrier
	s_waitcnt lgkmcnt(0)
	s_setprio 1
	s_waitcnt lgkmcnt(0)
	v_mfma_f32_16x16x32_bf16 v[122:125], v[204:207], v[162:165], v[122:125]
	v_mfma_f32_16x16x32_bf16 v[118:121], v[212:215], v[162:165], v[118:121]
	v_mfma_f32_16x16x32_bf16 v[106:109], v[204:207], v[170:173], v[106:109]
	v_mfma_f32_16x16x32_bf16 v[102:105], v[212:215], v[170:173], v[102:105]
	v_mfma_f32_16x16x32_bf16 v[90:93], v[204:207], v[178:181], v[90:93]
	v_mfma_f32_16x16x32_bf16 v[86:89], v[212:215], v[178:181], v[86:89]
	v_mfma_f32_16x16x32_bf16 v[74:77], v[204:207], v[196:199], v[74:77]
	v_mfma_f32_16x16x32_bf16 v[70:73], v[212:215], v[196:199], v[70:73]
	v_mfma_f32_16x16x32_bf16 v[122:125], v[208:211], v[166:169], v[122:125]
	v_mfma_f32_16x16x32_bf16 v[118:121], v[216:219], v[166:169], v[118:121]
	v_mfma_f32_16x16x32_bf16 v[106:109], v[208:211], v[174:177], v[106:109]
	v_mfma_f32_16x16x32_bf16 v[102:105], v[216:219], v[174:177], v[102:105]
	v_mfma_f32_16x16x32_bf16 v[90:93], v[208:211], v[186:189], v[90:93]
	v_mfma_f32_16x16x32_bf16 v[86:89], v[216:219], v[186:189], v[86:89]
	v_mfma_f32_16x16x32_bf16 v[74:77], v[208:211], v[200:203], v[74:77]
	v_mfma_f32_16x16x32_bf16 v[70:73], v[216:219], v[200:203], v[70:73]
	s_setprio 0
	s_mov_b32 m0, s24
	v_lshl_add_u64 v[236:237], s[54:55], 0, v[12:13]
	s_barrier
	ds_read_b128 v[162:165], v157 offset:16384
	ds_read_b128 v[166:169], v157 offset:17408
	ds_read_b128 v[170:173], v157 offset:18432
	ds_read_b128 v[174:177], v157 offset:19456
	ds_read_b128 v[178:181], v157 offset:20480
	ds_read_b128 v[186:189], v157 offset:21504
	ds_read_b128 v[196:199], v157 offset:22528
	ds_read_b128 v[200:203], v157 offset:23552
	global_load_lds_dwordx4 v[236:237], off
	v_lshl_add_u64 v[238:239], s[54:55], 0, v[134:135]
	s_mov_b32 m0, s56
	s_nop 0
	global_load_lds_dwordx4 v[238:239], off
	s_barrier
	s_waitcnt lgkmcnt(0)
	s_setprio 1
	s_waitcnt lgkmcnt(0)
	v_mfma_f32_16x16x32_bf16 v[66:69], v[140:143], v[162:165], v[66:69]
	v_mfma_f32_16x16x32_bf16 v[62:65], v[148:151], v[162:165], v[62:65]
	v_mfma_f32_16x16x32_bf16 v[50:53], v[140:143], v[170:173], v[50:53]
	v_mfma_f32_16x16x32_bf16 v[46:49], v[148:151], v[170:173], v[46:49]
	v_mfma_f32_16x16x32_bf16 v[34:37], v[140:143], v[178:181], v[34:37]
	v_mfma_f32_16x16x32_bf16 v[30:33], v[148:151], v[178:181], v[30:33]
	v_mfma_f32_16x16x32_bf16 v[18:21], v[140:143], v[196:199], v[18:21]
	v_mfma_f32_16x16x32_bf16 v[8:11], v[148:151], v[196:199], v[8:11]
	v_mfma_f32_16x16x32_bf16 v[66:69], v[144:147], v[166:169], v[66:69]
	v_mfma_f32_16x16x32_bf16 v[62:65], v[158:161], v[166:169], v[62:65]
	v_mfma_f32_16x16x32_bf16 v[50:53], v[144:147], v[174:177], v[50:53]
	v_mfma_f32_16x16x32_bf16 v[46:49], v[158:161], v[174:177], v[46:49]
	v_mfma_f32_16x16x32_bf16 v[34:37], v[144:147], v[186:189], v[34:37]
	v_mfma_f32_16x16x32_bf16 v[30:33], v[158:161], v[186:189], v[30:33]
	v_mfma_f32_16x16x32_bf16 v[18:21], v[144:147], v[200:203], v[18:21]
	v_mfma_f32_16x16x32_bf16 v[8:11], v[158:161], v[200:203], v[8:11]
	s_setprio 0
	s_barrier
; #define PG8_STAGE(bufoff, gbase, voff) do { _Pragma("unroll") for (int _i = 0; _i < 2; ++_i) \
;         __builtin_amdgcn_global_load_lds((const unsigned*)((const char*)(gbase) + (voff)[_i]), (LAS unsigned*)(lds + (bufoff) + ldsw + _i * 8192), 16, 0, 0); } while (0)
; #define PG8_LDA(dst, b, h) do { _Pragma("unroll") for (int m = 0; m < 4; ++m) _Pragma("unroll") for (int k = 0; k < 2; ++k) dst[m][k] = *(const LAS bf16x8*)(lds + PG8_SA(b, h) + aoff + m * 2048 + k * 1024); } while (0)
; #define PG8_LDB(dst, b, h) do { _Pragma("unroll") for (int n = 0; n < 2; ++n) _Pragma("unroll") for (int k = 0; k < 2; ++k) dst[n][k] = *(const LAS bf16x8*)(lds + PG8_SB(b, h) + boff + n * 2048 + k * 1024); } while (0)
; #define PG8_MMA(ai, bj, At, Bt) do { __builtin_amdgcn_s_setprio(1); _Pragma("unroll") for (int m = 0; m < 4; ++m) _Pragma("unroll") for (int n = 0; n < 2; ++n) _Pragma("unroll") for (int k = 0; k < 2; ++k) \
;         acc[ai][bj][m][n] = __builtin_amdgcn_mfma_f32_16x16x32_bf16(Bt[n][k], At[m][k], acc[ai][bj][m][n], 0, 0, 0); __builtin_amdgcn_s_setprio(0); } while (0)
; #define PG8_WAIT_V(n) asm volatile("s_waitcnt vmcnt(" #n ")" ::: "memory")
; #define PG8_WAIT_L(n) asm volatile("s_waitcnt lgkmcnt(" #n ")" ::: "memory")
; #define PG8_BAR __builtin_amdgcn_s_barrier()
; #define PG8_SCHED __builtin_amdgcn_sched_barrier(0)
; template <class Epi, class Sched>
; __device__ __forceinline__ void gemm_phase(const int TID, LAS unsigned char* lds, const int lda, const int ldb, const Sched& S, const Epi& E) {
;     ...
;             PG8_STAGE(PG8_SB(0, 1), b2 + hB, voffB);
;             PG8_WAIT_V(6); PG8_BAR; PG8_MMA(1, 1, At, B1); PG8_BAR;
;             PG8_LDB(B0, 1, 0); PG8_SCHED; PG8_LDA(At, 1, 0); PG8_STAGE(PG8_SA(0, 1), a2 + hA, voffA);
;             PG8_WAIT_L(8); PG8_BAR; PG8_WAIT_L(0); PG8_MMA(0, 0, At, B0); PG8_BAR; PG8_SCHED;
;             PG8_LDB(B1, 1, 1); PG8_STAGE(PG8_SB(1, 0), b3, voffB);
;             PG8_BAR; PG8_WAIT_L(0); PG8_MMA(0, 1, At, B1); PG8_BAR;
;             PG8_LDA(At, 1, 1); PG8_STAGE(PG8_SA(1, 0), a3, voffA);
;             PG8_BAR; PG8_WAIT_L(0); PG8_MMA(1, 0, At, B0); PG8_BAR; PG8_SCHED;
	s_add_u32 s8, s52, 0x80000
	s_addc_u32 s9, s53, 0
	s_add_i32 s10, s11, s23
	v_lshl_add_u64 v[140:141], s[8:9], 0, v[12:13]
	s_mov_b32 m0, s10
	s_nop 0
	global_load_lds_dwordx4 v[140:141], off
	v_lshl_add_u64 v[140:141], s[8:9], 0, v[134:135]
	s_add_i32 m0, s10, 0x2000
	s_nop 0
	global_load_lds_dwordx4 v[140:141], off
	s_waitcnt vmcnt(6)
	s_barrier
	s_setprio 1
	v_add_u32_e32 v158, 0x18000, v155
	v_mfma_f32_16x16x32_bf16 v[58:61], v[204:207], v[162:165], v[58:61]
	v_mfma_f32_16x16x32_bf16 v[54:57], v[212:215], v[162:165], v[54:57]
	v_mfma_f32_16x16x32_bf16 v[42:45], v[204:207], v[170:173], v[42:45]
	v_mfma_f32_16x16x32_bf16 v[38:41], v[212:215], v[170:173], v[38:41]
	ds_read_b128 v[140:143], v158
	v_mfma_f32_16x16x32_bf16 v[26:29], v[204:207], v[178:181], v[26:29]
	v_mfma_f32_16x16x32_bf16 v[22:25], v[212:215], v[178:181], v[22:25]
	ds_read_b128 v[144:147], v158 offset:1024
	v_mfma_f32_16x16x32_bf16 v[4:7], v[204:207], v[196:199], v[4:7]
	v_mfma_f32_16x16x32_bf16 v[0:3], v[212:215], v[196:199], v[0:3]
	ds_read_b128 v[148:151], v158 offset:2048
	v_mfma_f32_16x16x32_bf16 v[58:61], v[208:211], v[166:169], v[58:61]
	v_mfma_f32_16x16x32_bf16 v[54:57], v[216:219], v[166:169], v[54:57]
	ds_read_b128 v[158:161], v158 offset:3072
	v_mfma_f32_16x16x32_bf16 v[42:45], v[208:211], v[174:177], v[42:45]
	v_mfma_f32_16x16x32_bf16 v[38:41], v[216:219], v[174:177], v[38:41]
	v_mfma_f32_16x16x32_bf16 v[26:29], v[208:211], v[186:189], v[26:29]
	v_mfma_f32_16x16x32_bf16 v[22:25], v[216:219], v[186:189], v[22:25]
	v_mfma_f32_16x16x32_bf16 v[4:7], v[208:211], v[200:203], v[4:7]
	v_mfma_f32_16x16x32_bf16 v[0:3], v[216:219], v[200:203], v[0:3]
	s_setprio 0
	s_add_i32 s10, 0, 0x18000
	s_barrier
	s_add_u32 s8, s54, 0x80000
	s_addc_u32 s9, s55, 0
	s_mov_b32 m0, s57
	v_lshl_add_u64 v[204:205], s[8:9], 0, v[12:13]
	ds_read_b128 v[162:165], v157 offset:32768
	ds_read_b128 v[166:169], v157 offset:33792
	ds_read_b128 v[170:173], v157 offset:34816
	ds_read_b128 v[174:177], v157 offset:35840
	ds_read_b128 v[178:181], v157 offset:36864
	ds_read_b128 v[186:189], v157 offset:37888
	ds_read_b128 v[196:199], v157 offset:38912
	ds_read_b128 v[200:203], v157 offset:39936
	global_load_lds_dwordx4 v[204:205], off
	v_lshl_add_u64 v[204:205], s[8:9], 0, v[134:135]
	s_mov_b32 m0, s58
	s_nop 0
	global_load_lds_dwordx4 v[204:205], off
	s_waitcnt lgkmcnt(8)
	s_barrier
	s_waitcnt lgkmcnt(0)
	s_setprio 1
	s_waitcnt lgkmcnt(0)
	v_mfma_f32_16x16x32_bf16 v[130:133], v[140:143], v[162:165], v[130:133]
	v_mfma_f32_16x16x32_bf16 v[126:129], v[148:151], v[162:165], v[126:129]
	v_mfma_f32_16x16x32_bf16 v[114:117], v[140:143], v[170:173], v[114:117]
	v_mfma_f32_16x16x32_bf16 v[110:113], v[148:151], v[170:173], v[110:113]
	v_mfma_f32_16x16x32_bf16 v[98:101], v[140:143], v[178:181], v[98:101]
	v_mfma_f32_16x16x32_bf16 v[94:97], v[148:151], v[178:181], v[94:97]
	v_mfma_f32_16x16x32_bf16 v[82:85], v[140:143], v[196:199], v[82:85]
	v_mfma_f32_16x16x32_bf16 v[78:81], v[148:151], v[196:199], v[78:81]
	v_mfma_f32_16x16x32_bf16 v[130:133], v[144:147], v[166:169], v[130:133]
	v_mfma_f32_16x16x32_bf16 v[126:129], v[158:161], v[166:169], v[126:129]
	v_mfma_f32_16x16x32_bf16 v[114:117], v[144:147], v[174:177], v[114:117]
	v_mfma_f32_16x16x32_bf16 v[110:113], v[158:161], v[174:177], v[110:113]
	v_mfma_f32_16x16x32_bf16 v[98:101], v[144:147], v[186:189], v[98:101]
	v_mfma_f32_16x16x32_bf16 v[94:97], v[158:161], v[186:189], v[94:97]
	v_mfma_f32_16x16x32_bf16 v[82:85], v[144:147], v[200:203], v[82:85]
	v_mfma_f32_16x16x32_bf16 v[78:81], v[158:161], v[200:203], v[78:81]
	s_setprio 0
	s_barrier
	s_add_i32 s11, 0, 0x1c000
	s_add_i32 s8, s10, s23
	v_add_u32_e32 v182, s11, v155
	v_lshl_add_u64 v[220:221], v[220:221], 0, s[36:37]
	s_mov_b32 m0, s8
	ds_read_b128 v[204:207], v182
	ds_read_b128 v[208:211], v182 offset:1024
	ds_read_b128 v[212:215], v182 offset:2048
	ds_read_b128 v[216:219], v182 offset:3072
	global_load_lds_dwordx4 v[220:221], off
	v_lshl_add_u64 v[220:221], v[222:223], 0, s[36:37]
	s_add_i32 m0, s8, 0x2000
	s_nop 0
	global_load_lds_dwordx4 v[220:221], off
	s_barrier
	s_waitcnt lgkmcnt(0)
	s_setprio 1
	s_waitcnt lgkmcnt(0)
	v_mfma_f32_16x16x32_bf16 v[122:125], v[204:207], v[162:165], v[122:125]
	v_mfma_f32_16x16x32_bf16 v[118:121], v[212:215], v[162:165], v[118:121]
	v_mfma_f32_16x16x32_bf16 v[106:109], v[204:207], v[170:173], v[106:109]
	v_mfma_f32_16x16x32_bf16 v[102:105], v[212:215], v[170:173], v[102:105]
	v_mfma_f32_16x16x32_bf16 v[90:93], v[204:207], v[178:181], v[90:93]
	v_mfma_f32_16x16x32_bf16 v[86:89], v[212:215], v[178:181], v[86:89]
	v_mfma_f32_16x16x32_bf16 v[74:77], v[204:207], v[196:199], v[74:77]
	v_mfma_f32_16x16x32_bf16 v[70:73], v[212:215], v[196:199], v[70:73]
	v_mfma_f32_16x16x32_bf16 v[122:125], v[208:211], v[166:169], v[122:125]
	v_mfma_f32_16x16x32_bf16 v[118:121], v[216:219], v[166:169], v[118:121]
	v_mfma_f32_16x16x32_bf16 v[106:109], v[208:211], v[174:177], v[106:109]
	v_mfma_f32_16x16x32_bf16 v[102:105], v[216:219], v[174:177], v[102:105]
	v_mfma_f32_16x16x32_bf16 v[90:93], v[208:211], v[186:189], v[90:93]
	v_mfma_f32_16x16x32_bf16 v[86:89], v[216:219], v[186:189], v[86:89]
	v_mfma_f32_16x16x32_bf16 v[74:77], v[208:211], v[200:203], v[74:77]
	v_mfma_f32_16x16x32_bf16 v[70:73], v[216:219], v[200:203], v[70:73]
	s_setprio 0
	s_mov_b32 m0, s59
	v_lshl_add_u64 v[220:221], v[236:237], 0, s[36:37]
	s_barrier
	ds_read_b128 v[162:165], v157 offset:49152
	ds_read_b128 v[166:169], v157 offset:50176
	ds_read_b128 v[170:173], v157 offset:51200
	ds_read_b128 v[174:177], v157 offset:52224
	ds_read_b128 v[178:181], v157 offset:53248
	ds_read_b128 v[186:189], v157 offset:54272
	ds_read_b128 v[196:199], v157 offset:55296
	ds_read_b128 v[200:203], v157 offset:56320
	global_load_lds_dwordx4 v[220:221], off
	v_lshl_add_u64 v[220:221], v[238:239], 0, s[36:37]
	s_mov_b32 m0, s60
	s_nop 0
	global_load_lds_dwordx4 v[220:221], off
	s_barrier
; #define PG8_STAGE(bufoff, gbase, voff) do { _Pragma("unroll") for (int _i = 0; _i < 2; ++_i) \
;         __builtin_amdgcn_global_load_lds((const unsigned*)((const char*)(gbase) + (voff)[_i]), (LAS unsigned*)(lds + (bufoff) + ldsw + _i * 8192), 16, 0, 0); } while (0)
; #define PG8_MMA(ai, bj, At, Bt) do { __builtin_amdgcn_s_setprio(1); _Pragma("unroll") for (int m = 0; m < 4; ++m) _Pragma("unroll") for (int n = 0; n < 2; ++n) _Pragma("unroll") for (int k = 0; k < 2; ++k) \
;         acc[ai][bj][m][n] = __builtin_amdgcn_mfma_f32_16x16x32_bf16(Bt[n][k], At[m][k], acc[ai][bj][m][n], 0, 0, 0); __builtin_amdgcn_s_setprio(0); } while (0)
; #define PG8_WAIT_V(n) asm volatile("s_waitcnt vmcnt(" #n ")" ::: "memory")
; #define PG8_WAIT_L(n) asm volatile("s_waitcnt lgkmcnt(" #n ")" ::: "memory")
; #define PG8_BAR __builtin_amdgcn_s_barrier()
; #define PG8_SCHED __builtin_amdgcn_sched_barrier(0)
; template <class Epi, class Sched>
; __device__ __forceinline__ void gemm_phase(const int TID, LAS unsigned char* lds, const int lda, const int ldb, const Sched& S, const Epi& E) {
;     ...
;             PG8_BAR; PG8_WAIT_L(0); PG8_MMA(1, 0, At, B0); PG8_BAR; PG8_SCHED;
;             PG8_STAGE(PG8_SB(1, 1), b3 + hB, voffB);
;             PG8_WAIT_V(6); PG8_BAR; PG8_MMA(1, 1, At, B1); PG8_BAR;
; __device__ __forceinline__ const float* src_row(const Params& p, int r) {
;     int s, pos; if (r < 8224) { s = r / 4112; pos = r - s * 4112; } else { const int t = r - 8224; const int q = t / 2064; s = 2 + q; pos = t - q * 2064; }
;     if (pos < 16) return p.in[2] + (size_t)pos * D;
;     return s < 2 ? p.in[0] + ((size_t)s * 4096 + (pos - 16)) * D : p.in[1] + ((size_t)(s - 2) * 2048 + (pos - 16)) * D;
	s_waitcnt lgkmcnt(0)
	s_setprio 1
	s_waitcnt lgkmcnt(0)
	v_mfma_f32_16x16x32_bf16 v[66:69], v[140:143], v[162:165], v[66:69]
	v_mfma_f32_16x16x32_bf16 v[62:65], v[148:151], v[162:165], v[62:65]
	v_mfma_f32_16x16x32_bf16 v[50:53], v[140:143], v[170:173], v[50:53]
	v_mfma_f32_16x16x32_bf16 v[46:49], v[148:151], v[170:173], v[46:49]
	v_mfma_f32_16x16x32_bf16 v[34:37], v[140:143], v[178:181], v[34:37]
	v_mfma_f32_16x16x32_bf16 v[30:33], v[148:151], v[178:181], v[30:33]
	v_mfma_f32_16x16x32_bf16 v[18:21], v[140:143], v[196:199], v[18:21]
	v_mfma_f32_16x16x32_bf16 v[8:11], v[148:151], v[196:199], v[8:11]
	v_mfma_f32_16x16x32_bf16 v[66:69], v[144:147], v[166:169], v[66:69]
	v_mfma_f32_16x16x32_bf16 v[62:65], v[158:161], v[166:169], v[62:65]
	v_mfma_f32_16x16x32_bf16 v[50:53], v[144:147], v[174:177], v[50:53]
	v_mfma_f32_16x16x32_bf16 v[46:49], v[158:161], v[174:177], v[46:49]
	v_mfma_f32_16x16x32_bf16 v[34:37], v[144:147], v[186:189], v[34:37]
	v_mfma_f32_16x16x32_bf16 v[30:33], v[158:161], v[186:189], v[30:33]
	v_mfma_f32_16x16x32_bf16 v[18:21], v[144:147], v[200:203], v[18:21]
	v_mfma_f32_16x16x32_bf16 v[8:11], v[158:161], v[200:203], v[8:11]
	s_setprio 0
	s_barrier
	s_add_u32 s8, s52, 0x80080
	s_addc_u32 s9, s53, 0
	s_add_i32 s10, s11, s23
	v_lshl_add_u64 v[140:141], s[8:9], 0, v[12:13]
	s_mov_b32 m0, s10
	s_nop 0
	global_load_lds_dwordx4 v[140:141], off
	v_lshl_add_u64 v[140:141], s[8:9], 0, v[134:135]
	s_add_i32 m0, s10, 0x2000
	s_nop 0
	global_load_lds_dwordx4 v[140:141], off
	s_waitcnt vmcnt(6)
	s_barrier
	s_setprio 1
	v_add_u32_e32 v158, 0x10000, v155
	v_mfma_f32_16x16x32_bf16 v[58:61], v[204:207], v[162:165], v[58:61]
	v_mfma_f32_16x16x32_bf16 v[54:57], v[212:215], v[162:165], v[54:57]
	v_mfma_f32_16x16x32_bf16 v[42:45], v[204:207], v[170:173], v[42:45]
	v_mfma_f32_16x16x32_bf16 v[38:41], v[212:215], v[170:173], v[38:41]
	ds_read_b128 v[140:143], v158
	v_mfma_f32_16x16x32_bf16 v[26:29], v[204:207], v[178:181], v[26:29]
	v_mfma_f32_16x16x32_bf16 v[22:25], v[212:215], v[178:181], v[22:25]
	ds_read_b128 v[144:147], v158 offset:1024
	v_mfma_f32_16x16x32_bf16 v[4:7], v[204:207], v[196:199], v[4:7]
	v_mfma_f32_16x16x32_bf16 v[0:3], v[212:215], v[196:199], v[0:3]
	ds_read_b128 v[148:151], v158 offset:2048
	v_mfma_f32_16x16x32_bf16 v[58:61], v[208:211], v[166:169], v[58:61]
	v_mfma_f32_16x16x32_bf16 v[54:57], v[216:219], v[166:169], v[54:57]
	ds_read_b128 v[158:161], v158 offset:3072
	v_mfma_f32_16x16x32_bf16 v[42:45], v[208:211], v[174:177], v[42:45]
	v_mfma_f32_16x16x32_bf16 v[38:41], v[216:219], v[174:177], v[38:41]
	v_mfma_f32_16x16x32_bf16 v[26:29], v[208:211], v[186:189], v[26:29]
	v_mfma_f32_16x16x32_bf16 v[22:25], v[216:219], v[186:189], v[22:25]
	v_mfma_f32_16x16x32_bf16 v[4:7], v[208:211], v[200:203], v[4:7]
	v_mfma_f32_16x16x32_bf16 v[0:3], v[216:219], v[200:203], v[0:3]
	s_setprio 0
	s_add_i32 s49, s49, 2
	s_add_u32 s41, s41, 0x100
	s_addc_u32 s43, s43, 0
	s_add_u32 s50, s50, 0x100
	s_addc_u32 s51, s51, 0
	s_cmp_gt_u32 s49, 29
	s_barrier
	s_cbranch_scc0 .Lk7_body
	s_waitcnt lgkmcnt(0)
	v_lshl_add_u32 v142, s48, 8, v154
	v_lshl_or_b32 v140, s63, 8, v156
	s_movk_i32 s8, 0x60a0
	v_ashrrev_i32_e32 v141, 31, v140
	v_cmp_gt_i32_e32 vcc, s8, v142
	s_and_saveexec_b64 s[48:49], vcc
	s_cbranch_execz .LBB0_44
	v_ashrrev_i32_e32 v143, 31, v142
	v_lshlrev_b64 v[144:145], 13, v[142:143]
	v_lshl_add_u64 v[144:145], s[94:95], 0, v[144:145]
	s_andn2_b64 vcc, exec, s[28:29]
	v_mov_b64_e32 v[146:147], v[144:145]
	s_cbranch_vccnz .LBB0_43
	s_movk_i32 s8, 0x201f
	v_cmp_lt_i32_e32 vcc, s8, v142
	s_and_saveexec_b64 s[8:9], vcc
	s_xor_b64 s[50:51], exec, s[8:9]
	v_add_u32_e32 v143, 0xffffdfe0, v142
	v_mul_u32_u24_e32 v146, 0x3f81, v143
	v_lshrrev_b32_e32 v146, 25, v146
	s_movk_i32 s8, 0xf7f0
	v_add_u32_e32 v148, 2, v146
	v_mad_i32_i24 v146, v146, s8, v143
	s_andn2_saveexec_b64 s[50:51], s[50:51]
	s_mov_b32 s8, 0x7f807f81
	v_mul_hi_i32 v143, v142, s8
	v_lshrrev_b32_e32 v146, 31, v143
	v_ashrrev_i32_e32 v143, 11, v143
	v_add_u32_e32 v148, v143, v146
	s_movk_i32 s8, 0xeff0
	v_mad_i32_i24 v146, v148, s8, v142
	s_or_b64 exec, exec, s[50:51]
	v_readlane_b32 s64, v254, 0
	v_readlane_b32 s68, v254, 4
	v_readlane_b32 s69, v254, 5
	v_cmp_lt_i32_e32 vcc, 15, v146
	v_readlane_b32 s65, v254, 1
	v_mov_b64_e32 v[150:151], s[68:69]
	v_readlane_b32 s66, v254, 2
	v_readlane_b32 s67, v254, 3
	v_readlane_b32 s70, v254, 6
	v_readlane_b32 s71, v254, 7
	v_readlane_b32 s72, v254, 8
	v_readlane_b32 s73, v254, 9
	v_readlane_b32 s74, v254, 10
	v_readlane_b32 s75, v254, 11
	v_readlane_b32 s76, v254, 12
	v_readlane_b32 s77, v254, 13
	v_readlane_b32 s78, v254, 14
	v_readlane_b32 s79, v254, 15
	s_and_saveexec_b64 s[8:9], vcc
	s_xor_b64 s[50:51], exec, s[8:9]
	s_cbranch_execz .LBB0_40
	v_cmp_lt_i32_e32 vcc, 1, v148
	v_add_u32_e32 v182, -16, v146
	s_and_saveexec_b64 s[8:9], vcc
	s_xor_b64 s[52:53], exec, s[8:9]
	s_cbranch_execz .LBB0_37
	v_add_u32_e32 v146, -2, v148
	v_mov_b32_e32 v147, v183
	v_readlane_b32 s64, v254, 0
	v_lshlrev_b64 v[146:147], 24, v[146:147]
	v_readlane_b32 s66, v254, 2
	v_readlane_b32 s67, v254, 3
	v_readlane_b32 s65, v254, 1
	v_readlane_b32 s68, v254, 4
	v_readlane_b32 s69, v254, 5
	v_readlane_b32 s70, v254, 6
	v_readlane_b32 s71, v254, 7
	v_readlane_b32 s72, v254, 8
	v_readlane_b32 s73, v254, 9
	v_readlane_b32 s74, v254, 10
	v_readlane_b32 s75, v254, 11
	v_readlane_b32 s76, v254, 12
	v_readlane_b32 s77, v254, 13
	v_readlane_b32 s78, v254, 14
	v_readlane_b32 s79, v254, 15
	v_lshl_add_u64 v[150:151], s[66:67], 0, v[146:147]
	v_mov_b64_e32 v[146:147], v[182:183]

; #define PG8_STAGE(bufoff, gbase, voff) do { _Pragma("unroll") for (int _i = 0; _i < 2; ++_i) \
;         __builtin_amdgcn_global_load_lds((const unsigned*)((const char*)(gbase) + (voff)[_i]), (LAS unsigned*)(lds + (bufoff) + ldsw + _i * 8192), 16, 0, 0); } while (0)
; #define PG8_LDA(dst, b, h) do { _Pragma("unroll") for (int m = 0; m < 4; ++m) _Pragma("unroll") for (int k = 0; k < 2; ++k) dst[m][k] = *(const LAS bf16x8*)(lds + PG8_SA(b, h) + aoff + m * 2048 + k * 1024); } while (0)
; #define PG8_LDB(dst, b, h) do { _Pragma("unroll") for (int n = 0; n < 2; ++n) _Pragma("unroll") for (int k = 0; k < 2; ++k) dst[n][k] = *(const LAS bf16x8*)(lds + PG8_SB(b, h) + boff + n * 2048 + k * 1024); } while (0)
; #define PG8_MMA(ai, bj, At, Bt) do { __builtin_amdgcn_s_setprio(1); _Pragma("unroll") for (int m = 0; m < 4; ++m) _Pragma("unroll") for (int n = 0; n < 2; ++n) _Pragma("unroll") for (int k = 0; k < 2; ++k) \
;         acc[ai][bj][m][n] = __builtin_amdgcn_mfma_f32_16x16x32_bf16(Bt[n][k], At[m][k], acc[ai][bj][m][n], 0, 0, 0); __builtin_amdgcn_s_setprio(0); } while (0)
; #define PG8_WAIT_L(n) asm volatile("s_waitcnt lgkmcnt(" #n ")" ::: "memory")
; #define PG8_BAR __builtin_amdgcn_s_barrier()
; #define PG8_SCHED __builtin_amdgcn_sched_barrier(0)
; template <class Epi, class Sched>
; __device__ __forceinline__ void gemm_phase(const int TID, LAS unsigned char* lds, const int lda, const int ldb, const Sched& S, const Epi& E) {
;     ...
;             PG8_LDB(B0, 0, 0); PG8_SCHED; PG8_LDA(At, 0, 0); PG8_STAGE(PG8_SA(1, 1), a1 + hA, voffA);
;             PG8_WAIT_L(8); PG8_BAR; PG8_WAIT_L(0); PG8_MMA(0, 0, At, B0); PG8_BAR; PG8_SCHED;
;             PG8_LDB(B1, 0, 1); PG8_STAGE(PG8_SB(0, 0), b2, voffB);
;             PG8_BAR; PG8_WAIT_L(0); PG8_MMA(0, 1, At, B1); PG8_BAR;
;             PG8_LDA(At, 0, 1); PG8_STAGE(PG8_SA(0, 0), a2, voffA);
;             PG8_BAR; PG8_WAIT_L(0); PG8_MMA(1, 0, At, B0); PG8_BAR; PG8_SCHED;
.Lk6_nozero:
.LBB0_236:
	v_add_u32_e32 v146, 0x10000, v238
	ds_read_b128 v[106:109], v146
	ds_read_b128 v[118:121], v146 offset:1024
	ds_read_b128 v[134:137], v146 offset:2048
	ds_read_b128 v[146:149], v146 offset:3072
.Lk6_body:
	s_add_i32 s70, s54, 2
	s_add_u32 s8, s52, 0xfff80080
	s_addc_u32 s9, s53, -1
	s_add_i32 s10, 0, 0x10000
	s_cmp_eq_u32 s45, s54
	s_cselect_b32 s54, s50, s47
	s_cselect_b32 s57, s49, s9
	s_cselect_b32 s56, s48, s8
	s_cselect_b32 s55, s51, s69
	v_lshl_add_u64 v[186:187], s[52:53], 0, v[204:205]
	s_add_i32 m0, s24, 0xc000
	ds_read_b128 v[150:153], v240
	ds_read_b128 v[154:157], v240 offset:1024
	ds_read_b128 v[158:161], v240 offset:2048
	ds_read_b128 v[162:165], v240 offset:3072
	ds_read_b128 v[166:169], v240 offset:4096
	ds_read_b128 v[170:173], v240 offset:5120
	ds_read_b128 v[174:177], v240 offset:6144
	ds_read_b128 v[178:181], v240 offset:7168
	global_load_lds_dwordx4 v[186:187], off
	v_lshl_add_u64 v[186:187], s[52:53], 0, v[202:203]
	s_add_i32 m0, s24, 0xe000
	s_nop 0
	global_load_lds_dwordx4 v[186:187], off
	s_waitcnt lgkmcnt(8)
	s_barrier
	s_waitcnt lgkmcnt(0)
	s_setprio 1
	s_waitcnt lgkmcnt(0)
	v_mfma_f32_16x16x32_bf16 v[142:145], v[106:109], v[150:153], v[142:145]
	v_mfma_f32_16x16x32_bf16 v[138:141], v[134:137], v[150:153], v[138:141]
	v_mfma_f32_16x16x32_bf16 v[122:125], v[106:109], v[158:161], v[122:125]
	v_mfma_f32_16x16x32_bf16 v[114:117], v[134:137], v[158:161], v[114:117]
	v_mfma_f32_16x16x32_bf16 v[98:101], v[106:109], v[166:169], v[98:101]
	v_mfma_f32_16x16x32_bf16 v[94:97], v[134:137], v[166:169], v[94:97]
	v_mfma_f32_16x16x32_bf16 v[82:85], v[106:109], v[174:177], v[82:85]
	v_mfma_f32_16x16x32_bf16 v[78:81], v[134:137], v[174:177], v[78:81]
	v_mfma_f32_16x16x32_bf16 v[142:145], v[118:121], v[154:157], v[142:145]
	v_mfma_f32_16x16x32_bf16 v[138:141], v[146:149], v[154:157], v[138:141]
	v_mfma_f32_16x16x32_bf16 v[122:125], v[118:121], v[162:165], v[122:125]
	v_mfma_f32_16x16x32_bf16 v[114:117], v[146:149], v[162:165], v[114:117]
	v_mfma_f32_16x16x32_bf16 v[98:101], v[118:121], v[170:173], v[98:101]
	v_mfma_f32_16x16x32_bf16 v[94:97], v[146:149], v[170:173], v[94:97]
	v_mfma_f32_16x16x32_bf16 v[82:85], v[118:121], v[178:181], v[82:85]
	v_mfma_f32_16x16x32_bf16 v[78:81], v[146:149], v[178:181], v[78:81]
	s_setprio 0
	s_barrier
	s_add_i32 s11, 0, 0x14000
	s_add_i32 s8, s10, s23
	v_add_u32_e32 v214, s11, v238
	v_lshl_add_u64 v[218:219], s[54:55], 0, v[182:183]
	s_mov_b32 m0, s8
	ds_read_b128 v[186:189], v214
	ds_read_b128 v[206:209], v214 offset:1024
	ds_read_b128 v[210:213], v214 offset:2048
	ds_read_b128 v[214:217], v214 offset:3072
	global_load_lds_dwordx4 v[218:219], off
	v_lshl_add_u64 v[220:221], s[54:55], 0, v[198:199]
	s_add_i32 m0, s8, 0x2000
	s_nop 0
	global_load_lds_dwordx4 v[220:221], off
	s_barrier
	s_waitcnt lgkmcnt(0)
	s_setprio 1
	s_waitcnt lgkmcnt(0)
	v_mfma_f32_16x16x32_bf16 v[130:133], v[186:189], v[150:153], v[130:133]
	v_mfma_f32_16x16x32_bf16 v[126:129], v[210:213], v[150:153], v[126:129]
	v_mfma_f32_16x16x32_bf16 v[110:113], v[186:189], v[158:161], v[110:113]
	v_mfma_f32_16x16x32_bf16 v[102:105], v[210:213], v[158:161], v[102:105]
	v_mfma_f32_16x16x32_bf16 v[90:93], v[186:189], v[166:169], v[90:93]
	v_mfma_f32_16x16x32_bf16 v[86:89], v[210:213], v[166:169], v[86:89]
	v_mfma_f32_16x16x32_bf16 v[74:77], v[186:189], v[174:177], v[74:77]
	v_mfma_f32_16x16x32_bf16 v[70:73], v[210:213], v[174:177], v[70:73]
	v_mfma_f32_16x16x32_bf16 v[130:133], v[206:209], v[154:157], v[130:133]
	v_mfma_f32_16x16x32_bf16 v[126:129], v[214:217], v[154:157], v[126:129]
	v_mfma_f32_16x16x32_bf16 v[110:113], v[206:209], v[162:165], v[110:113]
	v_mfma_f32_16x16x32_bf16 v[102:105], v[214:217], v[162:165], v[102:105]
	v_mfma_f32_16x16x32_bf16 v[90:93], v[206:209], v[170:173], v[90:93]
	v_mfma_f32_16x16x32_bf16 v[86:89], v[214:217], v[170:173], v[86:89]
	v_mfma_f32_16x16x32_bf16 v[74:77], v[206:209], v[178:181], v[74:77]
	v_mfma_f32_16x16x32_bf16 v[70:73], v[214:217], v[178:181], v[70:73]
	s_setprio 0
	s_mov_b32 m0, s24
	v_lshl_add_u64 v[222:223], s[56:57], 0, v[12:13]
	s_barrier
	ds_read_b128 v[150:153], v240 offset:16384
	ds_read_b128 v[154:157], v240 offset:17408
	ds_read_b128 v[158:161], v240 offset:18432
	ds_read_b128 v[162:165], v240 offset:19456
	ds_read_b128 v[166:169], v240 offset:20480
	ds_read_b128 v[170:173], v240 offset:21504
	ds_read_b128 v[174:177], v240 offset:22528
	ds_read_b128 v[178:181], v240 offset:23552
	global_load_lds_dwordx4 v[222:223], off
	v_lshl_add_u64 v[242:243], s[56:57], 0, v[196:197]
	s_mov_b32 m0, s58
	s_nop 0
	global_load_lds_dwordx4 v[242:243], off
	s_barrier
	s_waitcnt lgkmcnt(0)
	s_setprio 1
	s_waitcnt lgkmcnt(0)
	v_mfma_f32_16x16x32_bf16 v[66:69], v[106:109], v[150:153], v[66:69]
	v_mfma_f32_16x16x32_bf16 v[62:65], v[134:137], v[150:153], v[62:65]
	v_mfma_f32_16x16x32_bf16 v[50:53], v[106:109], v[158:161], v[50:53]
	v_mfma_f32_16x16x32_bf16 v[46:49], v[134:137], v[158:161], v[46:49]
	v_mfma_f32_16x16x32_bf16 v[34:37], v[106:109], v[166:169], v[34:37]
	v_mfma_f32_16x16x32_bf16 v[30:33], v[134:137], v[166:169], v[30:33]
	v_mfma_f32_16x16x32_bf16 v[18:21], v[106:109], v[174:177], v[18:21]
	v_mfma_f32_16x16x32_bf16 v[8:11], v[134:137], v[174:177], v[8:11]
	v_mfma_f32_16x16x32_bf16 v[66:69], v[118:121], v[154:157], v[66:69]
	v_mfma_f32_16x16x32_bf16 v[62:65], v[146:149], v[154:157], v[62:65]
	v_mfma_f32_16x16x32_bf16 v[50:53], v[118:121], v[162:165], v[50:53]
	v_mfma_f32_16x16x32_bf16 v[46:49], v[146:149], v[162:165], v[46:49]
	v_mfma_f32_16x16x32_bf16 v[34:37], v[118:121], v[170:173], v[34:37]
	v_mfma_f32_16x16x32_bf16 v[30:33], v[146:149], v[170:173], v[30:33]
	v_mfma_f32_16x16x32_bf16 v[18:21], v[118:121], v[178:181], v[18:21]
	v_mfma_f32_16x16x32_bf16 v[8:11], v[146:149], v[178:181], v[8:11]
	s_setprio 0
	s_barrier
; #define PG8_STAGE(bufoff, gbase, voff) do { _Pragma("unroll") for (int _i = 0; _i < 2; ++_i) \
;         __builtin_amdgcn_global_load_lds((const unsigned*)((const char*)(gbase) + (voff)[_i]), (LAS unsigned*)(lds + (bufoff) + ldsw + _i * 8192), 16, 0, 0); } while (0)
; #define PG8_LDA(dst, b, h) do { _Pragma("unroll") for (int m = 0; m < 4; ++m) _Pragma("unroll") for (int k = 0; k < 2; ++k) dst[m][k] = *(const LAS bf16x8*)(lds + PG8_SA(b, h) + aoff + m * 2048 + k * 1024); } while (0)
; #define PG8_LDB(dst, b, h) do { _Pragma("unroll") for (int n = 0; n < 2; ++n) _Pragma("unroll") for (int k = 0; k < 2; ++k) dst[n][k] = *(const LAS bf16x8*)(lds + PG8_SB(b, h) + boff + n * 2048 + k * 1024); } while (0)
; #define PG8_MMA(ai, bj, At, Bt) do { __builtin_amdgcn_s_setprio(1); _Pragma("unroll") for (int m = 0; m < 4; ++m) _Pragma("unroll") for (int n = 0; n < 2; ++n) _Pragma("unroll") for (int k = 0; k < 2; ++k) \
;         acc[ai][bj][m][n] = __builtin_amdgcn_mfma_f32_16x16x32_bf16(Bt[n][k], At[m][k], acc[ai][bj][m][n], 0, 0, 0); __builtin_amdgcn_s_setprio(0); } while (0)
; #define PG8_WAIT_V(n) asm volatile("s_waitcnt vmcnt(" #n ")" ::: "memory")
; #define PG8_WAIT_L(n) asm volatile("s_waitcnt lgkmcnt(" #n ")" ::: "memory")
; #define PG8_BAR __builtin_amdgcn_s_barrier()
; #define PG8_SCHED __builtin_amdgcn_sched_barrier(0)
; template <class Epi, class Sched>
; __device__ __forceinline__ void gemm_phase(const int TID, LAS unsigned char* lds, const int lda, const int ldb, const Sched& S, const Epi& E) {
;     ...
;             PG8_STAGE(PG8_SB(0, 1), b2 + hB, voffB);
;             PG8_WAIT_V(6); PG8_BAR; PG8_MMA(1, 1, At, B1); PG8_BAR;
;             PG8_LDB(B0, 1, 0); PG8_SCHED; PG8_LDA(At, 1, 0); PG8_STAGE(PG8_SA(0, 1), a2 + hA, voffA);
;             PG8_WAIT_L(8); PG8_BAR; PG8_WAIT_L(0); PG8_MMA(0, 0, At, B0); PG8_BAR; PG8_SCHED;
;             PG8_LDB(B1, 1, 1); PG8_STAGE(PG8_SB(1, 0), b3, voffB);
;             PG8_BAR; PG8_WAIT_L(0); PG8_MMA(0, 1, At, B1); PG8_BAR;
;             PG8_LDA(At, 1, 1); PG8_STAGE(PG8_SA(1, 0), a3, voffA);
;             PG8_BAR; PG8_WAIT_L(0); PG8_MMA(1, 0, At, B0); PG8_BAR; PG8_SCHED;
	s_add_u32 s8, s54, 0x80000
	s_addc_u32 s9, s55, 0
	s_add_i32 s10, s11, s23
	v_lshl_add_u64 v[106:107], s[8:9], 0, v[182:183]
	s_mov_b32 m0, s10
	s_nop 0
	global_load_lds_dwordx4 v[106:107], off
	v_lshl_add_u64 v[106:107], s[8:9], 0, v[198:199]
	s_add_i32 m0, s10, 0x2000
	s_nop 0
	global_load_lds_dwordx4 v[106:107], off
	s_waitcnt vmcnt(6)
	s_barrier
	s_setprio 1
	v_add_u32_e32 v146, 0x18000, v238
	v_mfma_f32_16x16x32_bf16 v[58:61], v[186:189], v[150:153], v[58:61]
	v_mfma_f32_16x16x32_bf16 v[54:57], v[210:213], v[150:153], v[54:57]
	v_mfma_f32_16x16x32_bf16 v[42:45], v[186:189], v[158:161], v[42:45]
	v_mfma_f32_16x16x32_bf16 v[38:41], v[210:213], v[158:161], v[38:41]
	ds_read_b128 v[106:109], v146
	v_mfma_f32_16x16x32_bf16 v[26:29], v[186:189], v[166:169], v[26:29]
	v_mfma_f32_16x16x32_bf16 v[22:25], v[210:213], v[166:169], v[22:25]
	ds_read_b128 v[118:121], v146 offset:1024
	v_mfma_f32_16x16x32_bf16 v[4:7], v[186:189], v[174:177], v[4:7]
	v_mfma_f32_16x16x32_bf16 v[0:3], v[210:213], v[174:177], v[0:3]
	ds_read_b128 v[134:137], v146 offset:2048
	v_mfma_f32_16x16x32_bf16 v[58:61], v[206:209], v[154:157], v[58:61]
	v_mfma_f32_16x16x32_bf16 v[54:57], v[214:217], v[154:157], v[54:57]
	ds_read_b128 v[146:149], v146 offset:3072
	v_mfma_f32_16x16x32_bf16 v[42:45], v[206:209], v[162:165], v[42:45]
	v_mfma_f32_16x16x32_bf16 v[38:41], v[214:217], v[162:165], v[38:41]
	v_mfma_f32_16x16x32_bf16 v[26:29], v[206:209], v[170:173], v[26:29]
	v_mfma_f32_16x16x32_bf16 v[22:25], v[214:217], v[170:173], v[22:25]
	v_mfma_f32_16x16x32_bf16 v[4:7], v[206:209], v[178:181], v[4:7]
	v_mfma_f32_16x16x32_bf16 v[0:3], v[214:217], v[178:181], v[0:3]
	s_setprio 0
	s_add_i32 s10, 0, 0x18000
	s_barrier
	s_add_u32 s8, s56, 0x80000
	s_addc_u32 s9, s57, 0
	s_mov_b32 m0, s59
	v_lshl_add_u64 v[186:187], s[8:9], 0, v[12:13]
	ds_read_b128 v[150:153], v240 offset:32768
	ds_read_b128 v[154:157], v240 offset:33792
	ds_read_b128 v[158:161], v240 offset:34816
	ds_read_b128 v[162:165], v240 offset:35840
	ds_read_b128 v[166:169], v240 offset:36864
	ds_read_b128 v[170:173], v240 offset:37888
	ds_read_b128 v[174:177], v240 offset:38912
	ds_read_b128 v[178:181], v240 offset:39936
	global_load_lds_dwordx4 v[186:187], off
	v_lshl_add_u64 v[186:187], s[8:9], 0, v[196:197]
	s_mov_b32 m0, s60
	s_nop 0
	global_load_lds_dwordx4 v[186:187], off
	s_waitcnt lgkmcnt(8)
	s_barrier
	s_waitcnt lgkmcnt(0)
	s_setprio 1
	s_waitcnt lgkmcnt(0)
	v_mfma_f32_16x16x32_bf16 v[142:145], v[106:109], v[150:153], v[142:145]
	v_mfma_f32_16x16x32_bf16 v[138:141], v[134:137], v[150:153], v[138:141]
	v_mfma_f32_16x16x32_bf16 v[122:125], v[106:109], v[158:161], v[122:125]
	v_mfma_f32_16x16x32_bf16 v[114:117], v[134:137], v[158:161], v[114:117]
	v_mfma_f32_16x16x32_bf16 v[98:101], v[106:109], v[166:169], v[98:101]
	v_mfma_f32_16x16x32_bf16 v[94:97], v[134:137], v[166:169], v[94:97]
	v_mfma_f32_16x16x32_bf16 v[82:85], v[106:109], v[174:177], v[82:85]
	v_mfma_f32_16x16x32_bf16 v[78:81], v[134:137], v[174:177], v[78:81]
	v_mfma_f32_16x16x32_bf16 v[142:145], v[118:121], v[154:157], v[142:145]
	v_mfma_f32_16x16x32_bf16 v[138:141], v[146:149], v[154:157], v[138:141]
	v_mfma_f32_16x16x32_bf16 v[122:125], v[118:121], v[162:165], v[122:125]
	v_mfma_f32_16x16x32_bf16 v[114:117], v[146:149], v[162:165], v[114:117]
	v_mfma_f32_16x16x32_bf16 v[98:101], v[118:121], v[170:173], v[98:101]
	v_mfma_f32_16x16x32_bf16 v[94:97], v[146:149], v[170:173], v[94:97]
	v_mfma_f32_16x16x32_bf16 v[82:85], v[118:121], v[178:181], v[82:85]
	v_mfma_f32_16x16x32_bf16 v[78:81], v[146:149], v[178:181], v[78:81]
	s_setprio 0
	s_barrier
	s_add_i32 s11, 0, 0x1c000
	s_add_i32 s8, s10, s23
	v_add_u32_e32 v214, s11, v238
	v_lshl_add_u64 v[218:219], v[218:219], 0, s[36:37]
	s_mov_b32 m0, s8
	ds_read_b128 v[186:189], v214
	ds_read_b128 v[206:209], v214 offset:1024
	ds_read_b128 v[210:213], v214 offset:2048
	ds_read_b128 v[214:217], v214 offset:3072
	global_load_lds_dwordx4 v[218:219], off
	v_lshl_add_u64 v[218:219], v[220:221], 0, s[36:37]
	s_add_i32 m0, s8, 0x2000
	s_nop 0
	global_load_lds_dwordx4 v[218:219], off
	s_barrier
	s_waitcnt lgkmcnt(0)
	s_setprio 1
	s_waitcnt lgkmcnt(0)
	v_mfma_f32_16x16x32_bf16 v[130:133], v[186:189], v[150:153], v[130:133]
	v_mfma_f32_16x16x32_bf16 v[126:129], v[210:213], v[150:153], v[126:129]
	v_mfma_f32_16x16x32_bf16 v[110:113], v[186:189], v[158:161], v[110:113]
	v_mfma_f32_16x16x32_bf16 v[102:105], v[210:213], v[158:161], v[102:105]
	v_mfma_f32_16x16x32_bf16 v[90:93], v[186:189], v[166:169], v[90:93]
	v_mfma_f32_16x16x32_bf16 v[86:89], v[210:213], v[166:169], v[86:89]
	v_mfma_f32_16x16x32_bf16 v[74:77], v[186:189], v[174:177], v[74:77]
	v_mfma_f32_16x16x32_bf16 v[70:73], v[210:213], v[174:177], v[70:73]
	v_mfma_f32_16x16x32_bf16 v[130:133], v[206:209], v[154:157], v[130:133]
	v_mfma_f32_16x16x32_bf16 v[126:129], v[214:217], v[154:157], v[126:129]
	v_mfma_f32_16x16x32_bf16 v[110:113], v[206:209], v[162:165], v[110:113]
	v_mfma_f32_16x16x32_bf16 v[102:105], v[214:217], v[162:165], v[102:105]
	v_mfma_f32_16x16x32_bf16 v[90:93], v[206:209], v[170:173], v[90:93]
	v_mfma_f32_16x16x32_bf16 v[86:89], v[214:217], v[170:173], v[86:89]
	v_mfma_f32_16x16x32_bf16 v[74:77], v[206:209], v[178:181], v[74:77]
	v_mfma_f32_16x16x32_bf16 v[70:73], v[214:217], v[178:181], v[70:73]
	s_setprio 0
	s_mov_b32 m0, s61
	v_lshl_add_u64 v[218:219], v[222:223], 0, s[36:37]
	s_barrier
	ds_read_b128 v[150:153], v240 offset:49152
	ds_read_b128 v[154:157], v240 offset:50176
	ds_read_b128 v[158:161], v240 offset:51200
	ds_read_b128 v[162:165], v240 offset:52224
	ds_read_b128 v[166:169], v240 offset:53248
	ds_read_b128 v[170:173], v240 offset:54272
	ds_read_b128 v[174:177], v240 offset:55296
	ds_read_b128 v[178:181], v240 offset:56320
	global_load_lds_dwordx4 v[218:219], off
	v_lshl_add_u64 v[218:219], v[242:243], 0, s[36:37]
	s_mov_b32 m0, s62
	s_nop 0
	global_load_lds_dwordx4 v[218:219], off
	s_barrier
; #define PG8_STAGE(bufoff, gbase, voff) do { _Pragma("unroll") for (int _i = 0; _i < 2; ++_i) \
;         __builtin_amdgcn_global_load_lds((const unsigned*)((const char*)(gbase) + (voff)[_i]), (LAS unsigned*)(lds + (bufoff) + ldsw + _i * 8192), 16, 0, 0); } while (0)
; #define PG8_MMA(ai, bj, At, Bt) do { __builtin_amdgcn_s_setprio(1); _Pragma("unroll") for (int m = 0; m < 4; ++m) _Pragma("unroll") for (int n = 0; n < 2; ++n) _Pragma("unroll") for (int k = 0; k < 2; ++k) \
;         acc[ai][bj][m][n] = __builtin_amdgcn_mfma_f32_16x16x32_bf16(Bt[n][k], At[m][k], acc[ai][bj][m][n], 0, 0, 0); __builtin_amdgcn_s_setprio(0); } while (0)
; #define PG8_WAIT_V(n) asm volatile("s_waitcnt vmcnt(" #n ")" ::: "memory")
; #define PG8_WAIT_L(n) asm volatile("s_waitcnt lgkmcnt(" #n ")" ::: "memory")
; #define PG8_BAR __builtin_amdgcn_s_barrier()
; #define PG8_SCHED __builtin_amdgcn_sched_barrier(0)
; template <class Epi, class Sched>
; __device__ __forceinline__ void gemm_phase(const int TID, LAS unsigned char* lds, const int lda, const int ldb, const Sched& S, const Epi& E) {
;     ...
;             PG8_BAR; PG8_WAIT_L(0); PG8_MMA(1, 0, At, B0); PG8_BAR; PG8_SCHED;
;             PG8_STAGE(PG8_SB(1, 1), b3 + hB, voffB);
;             PG8_WAIT_V(6); PG8_BAR; PG8_MMA(1, 1, At, B1); PG8_BAR;
	s_waitcnt lgkmcnt(0)
	s_setprio 1
	s_waitcnt lgkmcnt(0)
	v_mfma_f32_16x16x32_bf16 v[66:69], v[106:109], v[150:153], v[66:69]
	v_mfma_f32_16x16x32_bf16 v[62:65], v[134:137], v[150:153], v[62:65]
	v_mfma_f32_16x16x32_bf16 v[50:53], v[106:109], v[158:161], v[50:53]
	v_mfma_f32_16x16x32_bf16 v[46:49], v[134:137], v[158:161], v[46:49]
	v_mfma_f32_16x16x32_bf16 v[34:37], v[106:109], v[166:169], v[34:37]
	v_mfma_f32_16x16x32_bf16 v[30:33], v[134:137], v[166:169], v[30:33]
	v_mfma_f32_16x16x32_bf16 v[18:21], v[106:109], v[174:177], v[18:21]
	v_mfma_f32_16x16x32_bf16 v[8:11], v[134:137], v[174:177], v[8:11]
	v_mfma_f32_16x16x32_bf16 v[66:69], v[118:121], v[154:157], v[66:69]
	v_mfma_f32_16x16x32_bf16 v[62:65], v[146:149], v[154:157], v[62:65]
	v_mfma_f32_16x16x32_bf16 v[50:53], v[118:121], v[162:165], v[50:53]
	v_mfma_f32_16x16x32_bf16 v[46:49], v[146:149], v[162:165], v[46:49]
	v_mfma_f32_16x16x32_bf16 v[34:37], v[118:121], v[170:173], v[34:37]
	v_mfma_f32_16x16x32_bf16 v[30:33], v[146:149], v[170:173], v[30:33]
	v_mfma_f32_16x16x32_bf16 v[18:21], v[118:121], v[178:181], v[18:21]
	v_mfma_f32_16x16x32_bf16 v[8:11], v[146:149], v[178:181], v[8:11]
	s_setprio 0
	s_barrier
	s_add_u32 s8, s54, 0x80080
	s_addc_u32 s9, s55, 0
	s_add_i32 s10, s11, s23
	v_lshl_add_u64 v[106:107], s[8:9], 0, v[182:183]
	s_mov_b32 m0, s10
	s_nop 0
	global_load_lds_dwordx4 v[106:107], off
	v_lshl_add_u64 v[106:107], s[8:9], 0, v[198:199]
	s_add_i32 m0, s10, 0x2000
	s_nop 0
	global_load_lds_dwordx4 v[106:107], off
	s_waitcnt vmcnt(6)
	s_barrier
	s_setprio 1
	v_add_u32_e32 v146, 0x10000, v238
	v_mfma_f32_16x16x32_bf16 v[58:61], v[186:189], v[150:153], v[58:61]
	v_mfma_f32_16x16x32_bf16 v[54:57], v[210:213], v[150:153], v[54:57]
	v_mfma_f32_16x16x32_bf16 v[42:45], v[186:189], v[158:161], v[42:45]
	v_mfma_f32_16x16x32_bf16 v[38:41], v[210:213], v[158:161], v[38:41]
	ds_read_b128 v[106:109], v146
	v_mfma_f32_16x16x32_bf16 v[26:29], v[186:189], v[166:169], v[26:29]
	v_mfma_f32_16x16x32_bf16 v[22:25], v[210:213], v[166:169], v[22:25]
	ds_read_b128 v[118:121], v146 offset:1024
	v_mfma_f32_16x16x32_bf16 v[4:7], v[186:189], v[174:177], v[4:7]
	v_mfma_f32_16x16x32_bf16 v[0:3], v[210:213], v[174:177], v[0:3]
	ds_read_b128 v[134:137], v146 offset:2048
	v_mfma_f32_16x16x32_bf16 v[58:61], v[206:209], v[154:157], v[58:61]
	v_mfma_f32_16x16x32_bf16 v[54:57], v[214:217], v[154:157], v[54:57]
	ds_read_b128 v[146:149], v146 offset:3072
	v_mfma_f32_16x16x32_bf16 v[42:45], v[206:209], v[162:165], v[42:45]
	v_mfma_f32_16x16x32_bf16 v[38:41], v[214:217], v[162:165], v[38:41]
	v_mfma_f32_16x16x32_bf16 v[26:29], v[206:209], v[170:173], v[26:29]
	v_mfma_f32_16x16x32_bf16 v[22:25], v[214:217], v[170:173], v[22:25]
	v_mfma_f32_16x16x32_bf16 v[4:7], v[206:209], v[178:181], v[4:7]
	v_mfma_f32_16x16x32_bf16 v[0:3], v[214:217], v[178:181], v[0:3]
	s_setprio 0
	s_add_u32 s47, s47, 0x100
	s_addc_u32 s69, s69, 0
	s_add_u32 s52, s52, 0x100
	s_addc_u32 s53, s53, 0
	s_cmp_ge_i32 s70, s68
	s_mov_b32 s54, s70
	s_barrier
	s_cbranch_scc0 .Lk6_body
	s_waitcnt lgkmcnt(0)
	s_cmp_eq_u32 s41, 2
	s_cbranch_scc1 .Lk6_final
	v_lshl_add_u32 v206, s40, 8, v237
	s_lshl_b32 s8, s41, 11
	s_lshl_b32 s9, s67, 8
	s_add_i32 s8, s8, s9
	s_addk_i32 s8, 0x2400
	s_add_u32 s10, s42, s8
	s_addc_u32 s11, s43, 0
	v_mad_u32_u24 v206, v206, s4, v200
	s_mov_b32 s9, 0x2f800000
	global_load_dwordx4 v[150:153], v206, s[10:11]
	global_load_dwordx4 v[106:109], v206, s[10:11] offset:2048
	s_add_u32 s10, s10, 0x56000
	s_addc_u32 s11, s11, 0
	global_load_dwordx4 v[154:157], v206, s[10:11]
	global_load_dwordx4 v[118:121], v206, s[10:11] offset:2048
	s_add_u32 s10, s10, 0x56000
	s_addc_u32 s11, s11, 0
	global_load_dwordx4 v[158:161], v206, s[10:11]
	global_load_dwordx4 v[134:137], v206, s[10:11] offset:2048
	s_add_u32 s10, s10, 0x56000
	s_addc_u32 s11, s11, 0
	global_load_dwordx4 v[162:165], v206, s[10:11]
	global_load_dwordx4 v[146:149], v206, s[10:11] offset:2048
	s_add_u32 s10, s10, 0x1ae000
	s_addc_u32 s11, s11, 0
	global_load_dwordx4 v[166:169], v206, s[10:11]
	global_load_dwordx4 v[186:189], v206, s[10:11] offset:2048
	s_add_u32 s10, s10, 0x56000
	s_addc_u32 s11, s11, 0
	global_load_dwordx4 v[170:173], v206, s[10:11]
	global_load_dwordx4 v[208:211], v206, s[10:11] offset:2048
	s_add_u32 s10, s10, 0x56000
	s_addc_u32 s11, s11, 0
	global_load_dwordx4 v[174:177], v206, s[10:11]
	global_load_dwordx4 v[212:215], v206, s[10:11] offset:2048
	s_add_u32 s10, s10, 0x56000
	s_addc_u32 s11, s11, 0
	global_load_dwordx4 v[178:181], v206, s[10:11]
	global_load_dwordx4 v[216:219], v206, s[10:11] offset:2048
	s_waitcnt vmcnt(14)
	v_cvt_f32_ubyte0_e32 v206, v106
	v_cvt_f32_ubyte1_e32 v207, v106
	v_cvt_f32_ubyte2_e32 v220, v106
	v_cvt_f32_ubyte3_e32 v221, v106
	v_cvt_f32_ubyte0_e32 v222, v150
	v_cvt_f32_ubyte1_e32 v223, v150
	v_cvt_f32_ubyte2_e32 v242, v150
	v_cvt_f32_ubyte3_e32 v243, v150
	v_max_f32_e32 v206, s9, v206
	v_max_f32_e32 v207, s9, v207
	v_max_f32_e32 v220, s9, v220
	v_max_f32_e32 v221, s9, v221
	v_max_f32_e32 v222, s9, v222
	v_max_f32_e32 v223, s9, v223
	v_max_f32_e32 v242, s9, v242
	v_max_f32_e32 v243, s9, v243
	v_rcp_f32_e32 v206, v206
	v_rcp_f32_e32 v207, v207
	v_rcp_f32_e32 v220, v220
	v_rcp_f32_e32 v221, v221
	v_mul_f32_e32 v222, v206, v222
	v_mul_f32_e32 v223, v207, v223
	v_mul_f32_e32 v242, v220, v242
	v_mul_f32_e32 v243, v221, v243
	v_mul_f32_e32 v142, v222, v142
	v_mul_f32_e32 v143, v223, v143
	v_mul_f32_e32 v144, v242, v144
	v_mul_f32_e32 v145, v243, v145
	v_cvt_f32_ubyte0_e32 v206, v107
	v_cvt_f32_ubyte1_e32 v207, v107
	v_cvt_f32_ubyte2_e32 v220, v107
	v_cvt_f32_ubyte3_e32 v221, v107
	v_cvt_f32_ubyte0_e32 v222, v151
	v_cvt_f32_ubyte1_e32 v223, v151
	v_cvt_f32_ubyte2_e32 v242, v151
	v_cvt_f32_ubyte3_e32 v243, v151
	v_max_f32_e32 v206, s9, v206
	v_max_f32_e32 v207, s9, v207
	v_max_f32_e32 v220, s9, v220
	v_max_f32_e32 v221, s9, v221
	v_max_f32_e32 v222, s9, v222
	v_max_f32_e32 v223, s9, v223
	v_max_f32_e32 v242, s9, v242
	v_max_f32_e32 v243, s9, v243
	v_rcp_f32_e32 v206, v206
	v_rcp_f32_e32 v207, v207
	v_rcp_f32_e32 v220, v220
	v_rcp_f32_e32 v221, v221
	v_mul_f32_e32 v222, v206, v222
	v_mul_f32_e32 v223, v207, v223
	v_mul_f32_e32 v242, v220, v242
	v_mul_f32_e32 v243, v221, v243
	v_mul_f32_e32 v138, v222, v138
	v_mul_f32_e32 v139, v223, v139
	v_mul_f32_e32 v140, v242, v140
	v_mul_f32_e32 v141, v243, v141
	v_cvt_f32_ubyte0_e32 v206, v108
	v_cvt_f32_ubyte1_e32 v207, v108
	v_cvt_f32_ubyte2_e32 v220, v108
	v_cvt_f32_ubyte3_e32 v221, v108
	v_cvt_f32_ubyte0_e32 v222, v152
	v_cvt_f32_ubyte1_e32 v223, v152
	v_cvt_f32_ubyte2_e32 v242, v152
	v_cvt_f32_ubyte3_e32 v243, v152
	v_max_f32_e32 v206, s9, v206
	v_max_f32_e32 v207, s9, v207
	v_max_f32_e32 v220, s9, v220
	v_max_f32_e32 v221, s9, v221
	v_max_f32_e32 v222, s9, v222
	v_max_f32_e32 v223, s9, v223
	v_max_f32_e32 v242, s9, v242
	v_max_f32_e32 v243, s9, v243
	v_rcp_f32_e32 v206, v206
	v_rcp_f32_e32 v207, v207
	v_rcp_f32_e32 v220, v220
	v_rcp_f32_e32 v221, v221
	v_mul_f32_e32 v222, v206, v222
	v_mul_f32_e32 v223, v207, v223
	v_mul_f32_e32 v242, v220, v242
	v_mul_f32_e32 v243, v221, v243
	v_mul_f32_e32 v130, v222, v130
	v_mul_f32_e32 v131, v223, v131
	v_mul_f32_e32 v132, v242, v132
	v_mul_f32_e32 v133, v243, v133
	v_cvt_f32_ubyte0_e32 v206, v109
	v_cvt_f32_ubyte1_e32 v207, v109
	v_cvt_f32_ubyte2_e32 v220, v109
	v_cvt_f32_ubyte3_e32 v221, v109
	v_cvt_f32_ubyte0_e32 v222, v153
	v_cvt_f32_ubyte1_e32 v223, v153
	v_cvt_f32_ubyte2_e32 v242, v153
	v_cvt_f32_ubyte3_e32 v243, v153
	v_max_f32_e32 v206, s9, v206
	v_max_f32_e32 v207, s9, v207
	v_max_f32_e32 v220, s9, v220
	v_max_f32_e32 v221, s9, v221
	v_max_f32_e32 v222, s9, v222
	v_max_f32_e32 v223, s9, v223
	v_max_f32_e32 v242, s9, v242
	v_max_f32_e32 v243, s9, v243
	v_rcp_f32_e32 v206, v206
	v_rcp_f32_e32 v207, v207
	v_rcp_f32_e32 v220, v220
	v_rcp_f32_e32 v221, v221
	v_mul_f32_e32 v222, v206, v222
	v_mul_f32_e32 v223, v207, v223
	v_mul_f32_e32 v242, v220, v242
	v_mul_f32_e32 v243, v221, v243
	v_mul_f32_e32 v126, v222, v126
	v_mul_f32_e32 v127, v223, v127
	v_mul_f32_e32 v128, v242, v128
	v_mul_f32_e32 v129, v243, v129
	s_waitcnt vmcnt(12)
	v_cvt_f32_ubyte0_e32 v206, v118
	v_cvt_f32_ubyte1_e32 v207, v118
	v_cvt_f32_ubyte2_e32 v220, v118
	v_cvt_f32_ubyte3_e32 v221, v118
	v_cvt_f32_ubyte0_e32 v222, v154
	v_cvt_f32_ubyte1_e32 v223, v154
	v_cvt_f32_ubyte2_e32 v242, v154
	v_cvt_f32_ubyte3_e32 v243, v154
	v_max_f32_e32 v206, s9, v206
	v_max_f32_e32 v207, s9, v207
	v_max_f32_e32 v220, s9, v220
	v_max_f32_e32 v221, s9, v221
	v_max_f32_e32 v222, s9, v222
	v_max_f32_e32 v223, s9, v223
	v_max_f32_e32 v242, s9, v242
	v_max_f32_e32 v243, s9, v243
	v_rcp_f32_e32 v206, v206
	v_rcp_f32_e32 v207, v207
	v_rcp_f32_e32 v220, v220
	v_rcp_f32_e32 v221, v221
	v_mul_f32_e32 v222, v206, v222
	v_mul_f32_e32 v223, v207, v223
	v_mul_f32_e32 v242, v220, v242
	v_mul_f32_e32 v243, v221, v243
	v_mul_f32_e32 v122, v222, v122
	v_mul_f32_e32 v123, v223, v123
	v_mul_f32_e32 v124, v242, v124
	v_mul_f32_e32 v125, v243, v125
	v_cvt_f32_ubyte0_e32 v206, v119
	v_cvt_f32_ubyte1_e32 v207, v119
	v_cvt_f32_ubyte2_e32 v220, v119
	v_cvt_f32_ubyte3_e32 v221, v119
	v_cvt_f32_ubyte0_e32 v222, v155
	v_cvt_f32_ubyte1_e32 v223, v155
	v_cvt_f32_ubyte2_e32 v242, v155
	v_cvt_f32_ubyte3_e32 v243, v155
	v_max_f32_e32 v206, s9, v206
	v_max_f32_e32 v207, s9, v207
	v_max_f32_e32 v220, s9, v220
	v_max_f32_e32 v221, s9, v221
	v_max_f32_e32 v222, s9, v222
	v_max_f32_e32 v223, s9, v223
	v_max_f32_e32 v242, s9, v242
	v_max_f32_e32 v243, s9, v243
	v_rcp_f32_e32 v206, v206
	v_rcp_f32_e32 v207, v207
	v_rcp_f32_e32 v220, v220
	v_rcp_f32_e32 v221, v221
	v_mul_f32_e32 v222, v206, v222
	v_mul_f32_e32 v223, v207, v223
	v_mul_f32_e32 v242, v220, v242
	v_mul_f32_e32 v243, v221, v243
	v_mul_f32_e32 v114, v222, v114
	v_mul_f32_e32 v115, v223, v115
	v_mul_f32_e32 v116, v242, v116
	v_mul_f32_e32 v117, v243, v117
	v_cvt_f32_ubyte0_e32 v206, v120
	v_cvt_f32_ubyte1_e32 v207, v120
	v_cvt_f32_ubyte2_e32 v220, v120
	v_cvt_f32_ubyte3_e32 v221, v120
	v_cvt_f32_ubyte0_e32 v222, v156
	v_cvt_f32_ubyte1_e32 v223, v156
	v_cvt_f32_ubyte2_e32 v242, v156
	v_cvt_f32_ubyte3_e32 v243, v156
	v_max_f32_e32 v206, s9, v206
	v_max_f32_e32 v207, s9, v207
	v_max_f32_e32 v220, s9, v220
	v_max_f32_e32 v221, s9, v221
	v_max_f32_e32 v222, s9, v222
	v_max_f32_e32 v223, s9, v223
	v_max_f32_e32 v242, s9, v242
	v_max_f32_e32 v243, s9, v243
	v_rcp_f32_e32 v206, v206
	v_rcp_f32_e32 v207, v207
	v_rcp_f32_e32 v220, v220
	v_rcp_f32_e32 v221, v221
	v_mul_f32_e32 v222, v206, v222
	v_mul_f32_e32 v223, v207, v223
	v_mul_f32_e32 v242, v220, v242
	v_mul_f32_e32 v243, v221, v243
	v_mul_f32_e32 v110, v222, v110
	v_mul_f32_e32 v111, v223, v111
	v_mul_f32_e32 v112, v242, v112
	v_mul_f32_e32 v113, v243, v113
	v_cvt_f32_ubyte0_e32 v206, v121
	v_cvt_f32_ubyte1_e32 v207, v121
	v_cvt_f32_ubyte2_e32 v220, v121
	v_cvt_f32_ubyte3_e32 v221, v121
	v_cvt_f32_ubyte0_e32 v222, v157
	v_cvt_f32_ubyte1_e32 v223, v157
	v_cvt_f32_ubyte2_e32 v242, v157
	v_cvt_f32_ubyte3_e32 v243, v157
	v_max_f32_e32 v206, s9, v206
	v_max_f32_e32 v207, s9, v207
	v_max_f32_e32 v220, s9, v220
	v_max_f32_e32 v221, s9, v221
	v_max_f32_e32 v222, s9, v222
	v_max_f32_e32 v223, s9, v223
	v_max_f32_e32 v242, s9, v242
	v_max_f32_e32 v243, s9, v243
	v_rcp_f32_e32 v206, v206
	v_rcp_f32_e32 v207, v207
	v_rcp_f32_e32 v220, v220
	v_rcp_f32_e32 v221, v221
	v_mul_f32_e32 v222, v206, v222
	v_mul_f32_e32 v223, v207, v223
	v_mul_f32_e32 v242, v220, v242
	v_mul_f32_e32 v243, v221, v243
	v_mul_f32_e32 v102, v222, v102
	v_mul_f32_e32 v103, v223, v103
	v_mul_f32_e32 v104, v242, v104
	v_mul_f32_e32 v105, v243, v105
	s_waitcnt vmcnt(10)
	v_cvt_f32_ubyte0_e32 v206, v134
	v_cvt_f32_ubyte1_e32 v207, v134
	v_cvt_f32_ubyte2_e32 v220, v134
	v_cvt_f32_ubyte3_e32 v221, v134
	v_cvt_f32_ubyte0_e32 v222, v158
	v_cvt_f32_ubyte1_e32 v223, v158
	v_cvt_f32_ubyte2_e32 v242, v158
	v_cvt_f32_ubyte3_e32 v243, v158
	v_max_f32_e32 v206, s9, v206
	v_max_f32_e32 v207, s9, v207
	v_max_f32_e32 v220, s9, v220
	v_max_f32_e32 v221, s9, v221
	v_max_f32_e32 v222, s9, v222
	v_max_f32_e32 v223, s9, v223
	v_max_f32_e32 v242, s9, v242
	v_max_f32_e32 v243, s9, v243
	v_rcp_f32_e32 v206, v206
	v_rcp_f32_e32 v207, v207
	v_rcp_f32_e32 v220, v220
	v_rcp_f32_e32 v221, v221
	v_mul_f32_e32 v222, v206, v222
	v_mul_f32_e32 v223, v207, v223
	v_mul_f32_e32 v242, v220, v242
	v_mul_f32_e32 v243, v221, v243
	v_mul_f32_e32 v98, v222, v98
	v_mul_f32_e32 v99, v223, v99
	v_mul_f32_e32 v100, v242, v100
	v_mul_f32_e32 v101, v243, v101
	v_cvt_f32_ubyte0_e32 v206, v135
	v_cvt_f32_ubyte1_e32 v207, v135
	v_cvt_f32_ubyte2_e32 v220, v135
	v_cvt_f32_ubyte3_e32 v221, v135
	v_cvt_f32_ubyte0_e32 v222, v159
	v_cvt_f32_ubyte1_e32 v223, v159
	v_cvt_f32_ubyte2_e32 v242, v159
	v_cvt_f32_ubyte3_e32 v243, v159
	v_max_f32_e32 v206, s9, v206
	v_max_f32_e32 v207, s9, v207
	v_max_f32_e32 v220, s9, v220
	v_max_f32_e32 v221, s9, v221
	v_max_f32_e32 v222, s9, v222
	v_max_f32_e32 v223, s9, v223
	v_max_f32_e32 v242, s9, v242
	v_max_f32_e32 v243, s9, v243
	v_rcp_f32_e32 v206, v206
	v_rcp_f32_e32 v207, v207
	v_rcp_f32_e32 v220, v220
	v_rcp_f32_e32 v221, v221
	v_mul_f32_e32 v222, v206, v222
	v_mul_f32_e32 v223, v207, v223
	v_mul_f32_e32 v242, v220, v242
	v_mul_f32_e32 v243, v221, v243
	v_mul_f32_e32 v94, v222, v94
	v_mul_f32_e32 v95, v223, v95
	v_mul_f32_e32 v96, v242, v96
	v_mul_f32_e32 v97, v243, v97
	v_cvt_f32_ubyte0_e32 v206, v136
	v_cvt_f32_ubyte1_e32 v207, v136
	v_cvt_f32_ubyte2_e32 v220, v136
	v_cvt_f32_ubyte3_e32 v221, v136
	v_cvt_f32_ubyte0_e32 v222, v160
	v_cvt_f32_ubyte1_e32 v223, v160
	v_cvt_f32_ubyte2_e32 v242, v160
	v_cvt_f32_ubyte3_e32 v243, v160
	v_max_f32_e32 v206, s9, v206
	v_max_f32_e32 v207, s9, v207
	v_max_f32_e32 v220, s9, v220
	v_max_f32_e32 v221, s9, v221
	v_max_f32_e32 v222, s9, v222
	v_max_f32_e32 v223, s9, v223
	v_max_f32_e32 v242, s9, v242
	v_max_f32_e32 v243, s9, v243
	v_rcp_f32_e32 v206, v206
	v_rcp_f32_e32 v207, v207
	v_rcp_f32_e32 v220, v220
	v_rcp_f32_e32 v221, v221
	v_mul_f32_e32 v222, v206, v222
	v_mul_f32_e32 v223, v207, v223
	v_mul_f32_e32 v242, v220, v242
	v_mul_f32_e32 v243, v221, v243
	v_mul_f32_e32 v90, v222, v90
	v_mul_f32_e32 v91, v223, v91
	v_mul_f32_e32 v92, v242, v92
	v_mul_f32_e32 v93, v243, v93
	v_cvt_f32_ubyte0_e32 v206, v137
	v_cvt_f32_ubyte1_e32 v207, v137
	v_cvt_f32_ubyte2_e32 v220, v137
	v_cvt_f32_ubyte3_e32 v221, v137
	v_cvt_f32_ubyte0_e32 v222, v161
	v_cvt_f32_ubyte1_e32 v223, v161
	v_cvt_f32_ubyte2_e32 v242, v161
	v_cvt_f32_ubyte3_e32 v243, v161
	v_max_f32_e32 v206, s9, v206
	v_max_f32_e32 v207, s9, v207
	v_max_f32_e32 v220, s9, v220
	v_max_f32_e32 v221, s9, v221
	v_max_f32_e32 v222, s9, v222
	v_max_f32_e32 v223, s9, v223
	v_max_f32_e32 v242, s9, v242
	v_max_f32_e32 v243, s9, v243
	v_rcp_f32_e32 v206, v206
	v_rcp_f32_e32 v207, v207
	v_rcp_f32_e32 v220, v220
	v_rcp_f32_e32 v221, v221
	v_mul_f32_e32 v222, v206, v222
	v_mul_f32_e32 v223, v207, v223
	v_mul_f32_e32 v242, v220, v242
	v_mul_f32_e32 v243, v221, v243
	v_mul_f32_e32 v86, v222, v86
	v_mul_f32_e32 v87, v223, v87
	v_mul_f32_e32 v88, v242, v88
	v_mul_f32_e32 v89, v243, v89
	s_waitcnt vmcnt(8)
	v_cvt_f32_ubyte0_e32 v206, v146
	v_cvt_f32_ubyte1_e32 v207, v146
	v_cvt_f32_ubyte2_e32 v220, v146
	v_cvt_f32_ubyte3_e32 v221, v146
	v_cvt_f32_ubyte0_e32 v222, v162
	v_cvt_f32_ubyte1_e32 v223, v162
	v_cvt_f32_ubyte2_e32 v242, v162
	v_cvt_f32_ubyte3_e32 v243, v162
	v_max_f32_e32 v206, s9, v206
	v_max_f32_e32 v207, s9, v207
	v_max_f32_e32 v220, s9, v220
	v_max_f32_e32 v221, s9, v221
	v_max_f32_e32 v222, s9, v222
	v_max_f32_e32 v223, s9, v223
	v_max_f32_e32 v242, s9, v242
	v_max_f32_e32 v243, s9, v243
	v_rcp_f32_e32 v206, v206
	v_rcp_f32_e32 v207, v207
	v_rcp_f32_e32 v220, v220
	v_rcp_f32_e32 v221, v221
	v_mul_f32_e32 v222, v206, v222
	v_mul_f32_e32 v223, v207, v223
	v_mul_f32_e32 v242, v220, v242
	v_mul_f32_e32 v243, v221, v243
	v_mul_f32_e32 v82, v222, v82
	v_mul_f32_e32 v83, v223, v83
	v_mul_f32_e32 v84, v242, v84
	v_mul_f32_e32 v85, v243, v85
	v_cvt_f32_ubyte0_e32 v206, v147
	v_cvt_f32_ubyte1_e32 v207, v147
	v_cvt_f32_ubyte2_e32 v220, v147
	v_cvt_f32_ubyte3_e32 v221, v147
	v_cvt_f32_ubyte0_e32 v222, v163
	v_cvt_f32_ubyte1_e32 v223, v163
	v_cvt_f32_ubyte2_e32 v242, v163
	v_cvt_f32_ubyte3_e32 v243, v163
	v_max_f32_e32 v206, s9, v206
	v_max_f32_e32 v207, s9, v207
	v_max_f32_e32 v220, s9, v220
	v_max_f32_e32 v221, s9, v221
	v_max_f32_e32 v222, s9, v222
	v_max_f32_e32 v223, s9, v223
	v_max_f32_e32 v242, s9, v242
	v_max_f32_e32 v243, s9, v243
	v_rcp_f32_e32 v206, v206
	v_rcp_f32_e32 v207, v207
	v_rcp_f32_e32 v220, v220
	v_rcp_f32_e32 v221, v221
	v_mul_f32_e32 v222, v206, v222
	v_mul_f32_e32 v223, v207, v223
	v_mul_f32_e32 v242, v220, v242
	v_mul_f32_e32 v243, v221, v243
	v_mul_f32_e32 v78, v222, v78
	v_mul_f32_e32 v79, v223, v79
	v_mul_f32_e32 v80, v242, v80
	v_mul_f32_e32 v81, v243, v81
	v_cvt_f32_ubyte0_e32 v206, v148
	v_cvt_f32_ubyte1_e32 v207, v148
	v_cvt_f32_ubyte2_e32 v220, v148
	v_cvt_f32_ubyte3_e32 v221, v148
	v_cvt_f32_ubyte0_e32 v222, v164
	v_cvt_f32_ubyte1_e32 v223, v164
	v_cvt_f32_ubyte2_e32 v242, v164
	v_cvt_f32_ubyte3_e32 v243, v164
	v_max_f32_e32 v206, s9, v206
	v_max_f32_e32 v207, s9, v207
	v_max_f32_e32 v220, s9, v220
	v_max_f32_e32 v221, s9, v221
	v_max_f32_e32 v222, s9, v222
	v_max_f32_e32 v223, s9, v223
	v_max_f32_e32 v242, s9, v242
	v_max_f32_e32 v243, s9, v243
	v_rcp_f32_e32 v206, v206
	v_rcp_f32_e32 v207, v207
	v_rcp_f32_e32 v220, v220
	v_rcp_f32_e32 v221, v221
	v_mul_f32_e32 v222, v206, v222
	v_mul_f32_e32 v223, v207, v223
	v_mul_f32_e32 v242, v220, v242
	v_mul_f32_e32 v243, v221, v243
	v_mul_f32_e32 v74, v222, v74
	v_mul_f32_e32 v75, v223, v75
	v_mul_f32_e32 v76, v242, v76
	v_mul_f32_e32 v77, v243, v77
	v_cvt_f32_ubyte0_e32 v206, v149
	v_cvt_f32_ubyte1_e32 v207, v149
	v_cvt_f32_ubyte2_e32 v220, v149
	v_cvt_f32_ubyte3_e32 v221, v149
	v_cvt_f32_ubyte0_e32 v222, v165
	v_cvt_f32_ubyte1_e32 v223, v165
	v_cvt_f32_ubyte2_e32 v242, v165
	v_cvt_f32_ubyte3_e32 v243, v165
	v_max_f32_e32 v206, s9, v206
	v_max_f32_e32 v207, s9, v207
	v_max_f32_e32 v220, s9, v220
	v_max_f32_e32 v221, s9, v221
	v_max_f32_e32 v222, s9, v222
	v_max_f32_e32 v223, s9, v223
	v_max_f32_e32 v242, s9, v242
	v_max_f32_e32 v243, s9, v243
	v_rcp_f32_e32 v206, v206
	v_rcp_f32_e32 v207, v207
	v_rcp_f32_e32 v220, v220
	v_rcp_f32_e32 v221, v221
	v_mul_f32_e32 v222, v206, v222
	v_mul_f32_e32 v223, v207, v223
	v_mul_f32_e32 v242, v220, v242
	v_mul_f32_e32 v243, v221, v243
	v_mul_f32_e32 v70, v222, v70
	v_mul_f32_e32 v71, v223, v71
	v_mul_f32_e32 v72, v242, v72
	v_mul_f32_e32 v73, v243, v73
	s_waitcnt vmcnt(6)
	v_cvt_f32_ubyte0_e32 v206, v186
	v_cvt_f32_ubyte1_e32 v207, v186
	v_cvt_f32_ubyte2_e32 v220, v186
	v_cvt_f32_ubyte3_e32 v221, v186
	v_cvt_f32_ubyte0_e32 v222, v166
	v_cvt_f32_ubyte1_e32 v223, v166
	v_cvt_f32_ubyte2_e32 v242, v166
	v_cvt_f32_ubyte3_e32 v243, v166
	v_max_f32_e32 v206, s9, v206
	v_max_f32_e32 v207, s9, v207
	v_max_f32_e32 v220, s9, v220
	v_max_f32_e32 v221, s9, v221
	v_max_f32_e32 v222, s9, v222
	v_max_f32_e32 v223, s9, v223
	v_max_f32_e32 v242, s9, v242
	v_max_f32_e32 v243, s9, v243
	v_rcp_f32_e32 v206, v206
	v_rcp_f32_e32 v207, v207
	v_rcp_f32_e32 v220, v220
	v_rcp_f32_e32 v221, v221
	v_mul_f32_e32 v222, v206, v222
	v_mul_f32_e32 v223, v207, v223
	v_mul_f32_e32 v242, v220, v242
	v_mul_f32_e32 v243, v221, v243
	v_mul_f32_e32 v66, v222, v66
	v_mul_f32_e32 v67, v223, v67
	v_mul_f32_e32 v68, v242, v68
	v_mul_f32_e32 v69, v243, v69
	v_cvt_f32_ubyte0_e32 v206, v187
	v_cvt_f32_ubyte1_e32 v207, v187
	v_cvt_f32_ubyte2_e32 v220, v187
	v_cvt_f32_ubyte3_e32 v221, v187
	v_cvt_f32_ubyte0_e32 v222, v167
	v_cvt_f32_ubyte1_e32 v223, v167
	v_cvt_f32_ubyte2_e32 v242, v167
	v_cvt_f32_ubyte3_e32 v243, v167
	v_max_f32_e32 v206, s9, v206
	v_max_f32_e32 v207, s9, v207
	v_max_f32_e32 v220, s9, v220
	v_max_f32_e32 v221, s9, v221
	v_max_f32_e32 v222, s9, v222
	v_max_f32_e32 v223, s9, v223
	v_max_f32_e32 v242, s9, v242
	v_max_f32_e32 v243, s9, v243
	v_rcp_f32_e32 v206, v206
	v_rcp_f32_e32 v207, v207
	v_rcp_f32_e32 v220, v220
	v_rcp_f32_e32 v221, v221
	v_mul_f32_e32 v222, v206, v222
	v_mul_f32_e32 v223, v207, v223
	v_mul_f32_e32 v242, v220, v242
	v_mul_f32_e32 v243, v221, v243
	v_mul_f32_e32 v62, v222, v62
	v_mul_f32_e32 v63, v223, v63
	v_mul_f32_e32 v64, v242, v64
	v_mul_f32_e32 v65, v243, v65
	v_cvt_f32_ubyte0_e32 v206, v188
	v_cvt_f32_ubyte1_e32 v207, v188
	v_cvt_f32_ubyte2_e32 v220, v188
	v_cvt_f32_ubyte3_e32 v221, v188
	v_cvt_f32_ubyte0_e32 v222, v168
	v_cvt_f32_ubyte1_e32 v223, v168
	v_cvt_f32_ubyte2_e32 v242, v168
	v_cvt_f32_ubyte3_e32 v243, v168
	v_max_f32_e32 v206, s9, v206
	v_max_f32_e32 v207, s9, v207
	v_max_f32_e32 v220, s9, v220
	v_max_f32_e32 v221, s9, v221
	v_max_f32_e32 v222, s9, v222
	v_max_f32_e32 v223, s9, v223
	v_max_f32_e32 v242, s9, v242
	v_max_f32_e32 v243, s9, v243
	v_rcp_f32_e32 v206, v206
	v_rcp_f32_e32 v207, v207
	v_rcp_f32_e32 v220, v220
	v_rcp_f32_e32 v221, v221
	v_mul_f32_e32 v222, v206, v222
	v_mul_f32_e32 v223, v207, v223
	v_mul_f32_e32 v242, v220, v242
	v_mul_f32_e32 v243, v221, v243
	v_mul_f32_e32 v58, v222, v58
	v_mul_f32_e32 v59, v223, v59
	v_mul_f32_e32 v60, v242, v60
	v_mul_f32_e32 v61, v243, v61
	v_cvt_f32_ubyte0_e32 v206, v189
	v_cvt_f32_ubyte1_e32 v207, v189
	v_cvt_f32_ubyte2_e32 v220, v189
	v_cvt_f32_ubyte3_e32 v221, v189
	v_cvt_f32_ubyte0_e32 v222, v169
	v_cvt_f32_ubyte1_e32 v223, v169
	v_cvt_f32_ubyte2_e32 v242, v169
	v_cvt_f32_ubyte3_e32 v243, v169
	v_max_f32_e32 v206, s9, v206
	v_max_f32_e32 v207, s9, v207
	v_max_f32_e32 v220, s9, v220
	v_max_f32_e32 v221, s9, v221
	v_max_f32_e32 v222, s9, v222
	v_max_f32_e32 v223, s9, v223
	v_max_f32_e32 v242, s9, v242
	v_max_f32_e32 v243, s9, v243
	v_rcp_f32_e32 v206, v206
	v_rcp_f32_e32 v207, v207
	v_rcp_f32_e32 v220, v220
	v_rcp_f32_e32 v221, v221
	v_mul_f32_e32 v222, v206, v222
	v_mul_f32_e32 v223, v207, v223
	v_mul_f32_e32 v242, v220, v242
	v_mul_f32_e32 v243, v221, v243
	v_mul_f32_e32 v54, v222, v54
	v_mul_f32_e32 v55, v223, v55
	v_mul_f32_e32 v56, v242, v56
	v_mul_f32_e32 v57, v243, v57
	s_waitcnt vmcnt(4)
	v_cvt_f32_ubyte0_e32 v206, v208
	v_cvt_f32_ubyte1_e32 v207, v208
	v_cvt_f32_ubyte2_e32 v220, v208
	v_cvt_f32_ubyte3_e32 v221, v208
	v_cvt_f32_ubyte0_e32 v222, v170
	v_cvt_f32_ubyte1_e32 v223, v170
	v_cvt_f32_ubyte2_e32 v242, v170
	v_cvt_f32_ubyte3_e32 v243, v170
	v_max_f32_e32 v206, s9, v206
	v_max_f32_e32 v207, s9, v207
	v_max_f32_e32 v220, s9, v220
	v_max_f32_e32 v221, s9, v221
	v_max_f32_e32 v222, s9, v222
	v_max_f32_e32 v223, s9, v223
	v_max_f32_e32 v242, s9, v242
	v_max_f32_e32 v243, s9, v243
	v_rcp_f32_e32 v206, v206
	v_rcp_f32_e32 v207, v207
	v_rcp_f32_e32 v220, v220
	v_rcp_f32_e32 v221, v221
	v_mul_f32_e32 v222, v206, v222
	v_mul_f32_e32 v223, v207, v223
	v_mul_f32_e32 v242, v220, v242
	v_mul_f32_e32 v243, v221, v243
	v_mul_f32_e32 v50, v222, v50
	v_mul_f32_e32 v51, v223, v51
	v_mul_f32_e32 v52, v242, v52
	v_mul_f32_e32 v53, v243, v53
	v_cvt_f32_ubyte0_e32 v206, v209
	v_cvt_f32_ubyte1_e32 v207, v209
	v_cvt_f32_ubyte2_e32 v220, v209
	v_cvt_f32_ubyte3_e32 v221, v209
	v_cvt_f32_ubyte0_e32 v222, v171
	v_cvt_f32_ubyte1_e32 v223, v171
	v_cvt_f32_ubyte2_e32 v242, v171
	v_cvt_f32_ubyte3_e32 v243, v171
	v_max_f32_e32 v206, s9, v206
	v_max_f32_e32 v207, s9, v207
	v_max_f32_e32 v220, s9, v220
	v_max_f32_e32 v221, s9, v221
	v_max_f32_e32 v222, s9, v222
	v_max_f32_e32 v223, s9, v223
	v_max_f32_e32 v242, s9, v242
	v_max_f32_e32 v243, s9, v243
	v_rcp_f32_e32 v206, v206
	v_rcp_f32_e32 v207, v207
	v_rcp_f32_e32 v220, v220
	v_rcp_f32_e32 v221, v221
	v_mul_f32_e32 v222, v206, v222
	v_mul_f32_e32 v223, v207, v223
	v_mul_f32_e32 v242, v220, v242
	v_mul_f32_e32 v243, v221, v243
	v_mul_f32_e32 v46, v222, v46
	v_mul_f32_e32 v47, v223, v47
	v_mul_f32_e32 v48, v242, v48
	v_mul_f32_e32 v49, v243, v49
	v_cvt_f32_ubyte0_e32 v206, v210
	v_cvt_f32_ubyte1_e32 v207, v210
	v_cvt_f32_ubyte2_e32 v220, v210
	v_cvt_f32_ubyte3_e32 v221, v210
	v_cvt_f32_ubyte0_e32 v222, v172
	v_cvt_f32_ubyte1_e32 v223, v172
	v_cvt_f32_ubyte2_e32 v242, v172
	v_cvt_f32_ubyte3_e32 v243, v172
	v_max_f32_e32 v206, s9, v206
	v_max_f32_e32 v207, s9, v207
	v_max_f32_e32 v220, s9, v220
	v_max_f32_e32 v221, s9, v221
	v_max_f32_e32 v222, s9, v222
	v_max_f32_e32 v223, s9, v223
	v_max_f32_e32 v242, s9, v242
	v_max_f32_e32 v243, s9, v243
	v_rcp_f32_e32 v206, v206
	v_rcp_f32_e32 v207, v207
	v_rcp_f32_e32 v220, v220
	v_rcp_f32_e32 v221, v221
	v_mul_f32_e32 v222, v206, v222
	v_mul_f32_e32 v223, v207, v223
	v_mul_f32_e32 v242, v220, v242
	v_mul_f32_e32 v243, v221, v243
	v_mul_f32_e32 v42, v222, v42
	v_mul_f32_e32 v43, v223, v43
	v_mul_f32_e32 v44, v242, v44
	v_mul_f32_e32 v45, v243, v45
	v_cvt_f32_ubyte0_e32 v206, v211
	v_cvt_f32_ubyte1_e32 v207, v211
	v_cvt_f32_ubyte2_e32 v220, v211
	v_cvt_f32_ubyte3_e32 v221, v211
	v_cvt_f32_ubyte0_e32 v222, v173
	v_cvt_f32_ubyte1_e32 v223, v173
	v_cvt_f32_ubyte2_e32 v242, v173
	v_cvt_f32_ubyte3_e32 v243, v173
	v_max_f32_e32 v206, s9, v206
	v_max_f32_e32 v207, s9, v207
	v_max_f32_e32 v220, s9, v220
	v_max_f32_e32 v221, s9, v221
	v_max_f32_e32 v222, s9, v222
	v_max_f32_e32 v223, s9, v223
	v_max_f32_e32 v242, s9, v242
	v_max_f32_e32 v243, s9, v243
	v_rcp_f32_e32 v206, v206
	v_rcp_f32_e32 v207, v207
	v_rcp_f32_e32 v220, v220
	v_rcp_f32_e32 v221, v221
	v_mul_f32_e32 v222, v206, v222
	v_mul_f32_e32 v223, v207, v223
	v_mul_f32_e32 v242, v220, v242
	v_mul_f32_e32 v243, v221, v243
	v_mul_f32_e32 v38, v222, v38
	v_mul_f32_e32 v39, v223, v39
	v_mul_f32_e32 v40, v242, v40
	v_mul_f32_e32 v41, v243, v41
	s_waitcnt vmcnt(2)
; template <class Epi, class Sched>
; __device__ __forceinline__ void gemm_phase(const int TID, LAS unsigned char* lds, const int lda, const int ldb, const Sched& S, const Epi& E) {
;     ...
;         cur = nxt; cA = nA; cB = nB; ++ui;
	v_cvt_f32_ubyte0_e32 v206, v212
	v_cvt_f32_ubyte1_e32 v207, v212
	v_cvt_f32_ubyte2_e32 v220, v212
	v_cvt_f32_ubyte3_e32 v221, v212
	v_cvt_f32_ubyte0_e32 v222, v174
	v_cvt_f32_ubyte1_e32 v223, v174
	v_cvt_f32_ubyte2_e32 v242, v174
	v_cvt_f32_ubyte3_e32 v243, v174
	v_max_f32_e32 v206, s9, v206
	v_max_f32_e32 v207, s9, v207
	v_max_f32_e32 v220, s9, v220
	v_max_f32_e32 v221, s9, v221
	v_max_f32_e32 v222, s9, v222
	v_max_f32_e32 v223, s9, v223
	v_max_f32_e32 v242, s9, v242
	v_max_f32_e32 v243, s9, v243
	v_rcp_f32_e32 v206, v206
	v_rcp_f32_e32 v207, v207
	v_rcp_f32_e32 v220, v220
	v_rcp_f32_e32 v221, v221
	v_mul_f32_e32 v222, v206, v222
	v_mul_f32_e32 v223, v207, v223
	v_mul_f32_e32 v242, v220, v242
	v_mul_f32_e32 v243, v221, v243
	v_mul_f32_e32 v34, v222, v34
	v_mul_f32_e32 v35, v223, v35
	v_mul_f32_e32 v36, v242, v36
	v_mul_f32_e32 v37, v243, v37
	v_cvt_f32_ubyte0_e32 v206, v213
	v_cvt_f32_ubyte1_e32 v207, v213
	v_cvt_f32_ubyte2_e32 v220, v213
	v_cvt_f32_ubyte3_e32 v221, v213
	v_cvt_f32_ubyte0_e32 v222, v175
	v_cvt_f32_ubyte1_e32 v223, v175
	v_cvt_f32_ubyte2_e32 v242, v175
	v_cvt_f32_ubyte3_e32 v243, v175
	v_max_f32_e32 v206, s9, v206
	v_max_f32_e32 v207, s9, v207
	v_max_f32_e32 v220, s9, v220
	v_max_f32_e32 v221, s9, v221
	v_max_f32_e32 v222, s9, v222
	v_max_f32_e32 v223, s9, v223
	v_max_f32_e32 v242, s9, v242
	v_max_f32_e32 v243, s9, v243
	v_rcp_f32_e32 v206, v206
	v_rcp_f32_e32 v207, v207
	v_rcp_f32_e32 v220, v220
	v_rcp_f32_e32 v221, v221
	v_mul_f32_e32 v222, v206, v222
	v_mul_f32_e32 v223, v207, v223
	v_mul_f32_e32 v242, v220, v242
	v_mul_f32_e32 v243, v221, v243
	v_mul_f32_e32 v30, v222, v30
	v_mul_f32_e32 v31, v223, v31
	v_mul_f32_e32 v32, v242, v32
	v_mul_f32_e32 v33, v243, v33
	v_cvt_f32_ubyte0_e32 v206, v214
	v_cvt_f32_ubyte1_e32 v207, v214
	v_cvt_f32_ubyte2_e32 v220, v214
	v_cvt_f32_ubyte3_e32 v221, v214
	v_cvt_f32_ubyte0_e32 v222, v176
	v_cvt_f32_ubyte1_e32 v223, v176
	v_cvt_f32_ubyte2_e32 v242, v176
	v_cvt_f32_ubyte3_e32 v243, v176
	v_max_f32_e32 v206, s9, v206
	v_max_f32_e32 v207, s9, v207
	v_max_f32_e32 v220, s9, v220
	v_max_f32_e32 v221, s9, v221
	v_max_f32_e32 v222, s9, v222
	v_max_f32_e32 v223, s9, v223
	v_max_f32_e32 v242, s9, v242
	v_max_f32_e32 v243, s9, v243
	v_rcp_f32_e32 v206, v206
	v_rcp_f32_e32 v207, v207
	v_rcp_f32_e32 v220, v220
	v_rcp_f32_e32 v221, v221
	v_mul_f32_e32 v222, v206, v222
	v_mul_f32_e32 v223, v207, v223
	v_mul_f32_e32 v242, v220, v242
	v_mul_f32_e32 v243, v221, v243
	v_mul_f32_e32 v26, v222, v26
	v_mul_f32_e32 v27, v223, v27
	v_mul_f32_e32 v28, v242, v28
	v_mul_f32_e32 v29, v243, v29
	v_cvt_f32_ubyte0_e32 v206, v215
	v_cvt_f32_ubyte1_e32 v207, v215
	v_cvt_f32_ubyte2_e32 v220, v215
	v_cvt_f32_ubyte3_e32 v221, v215
	v_cvt_f32_ubyte0_e32 v222, v177
	v_cvt_f32_ubyte1_e32 v223, v177
	v_cvt_f32_ubyte2_e32 v242, v177
	v_cvt_f32_ubyte3_e32 v243, v177
	v_max_f32_e32 v206, s9, v206
	v_max_f32_e32 v207, s9, v207
	v_max_f32_e32 v220, s9, v220
	v_max_f32_e32 v221, s9, v221
	v_max_f32_e32 v222, s9, v222
	v_max_f32_e32 v223, s9, v223
	v_max_f32_e32 v242, s9, v242
	v_max_f32_e32 v243, s9, v243
	v_rcp_f32_e32 v206, v206
	v_rcp_f32_e32 v207, v207
	v_rcp_f32_e32 v220, v220
	v_rcp_f32_e32 v221, v221
	v_mul_f32_e32 v222, v206, v222
	v_mul_f32_e32 v223, v207, v223
	v_mul_f32_e32 v242, v220, v242
	v_mul_f32_e32 v243, v221, v243
	v_mul_f32_e32 v22, v222, v22
	v_mul_f32_e32 v23, v223, v23
	v_mul_f32_e32 v24, v242, v24
	v_mul_f32_e32 v25, v243, v25
	s_waitcnt vmcnt(0)
	v_cvt_f32_ubyte0_e32 v206, v216
	v_cvt_f32_ubyte1_e32 v207, v216
	v_cvt_f32_ubyte2_e32 v220, v216
	v_cvt_f32_ubyte3_e32 v221, v216
	v_cvt_f32_ubyte0_e32 v222, v178
	v_cvt_f32_ubyte1_e32 v223, v178
	v_cvt_f32_ubyte2_e32 v242, v178
	v_cvt_f32_ubyte3_e32 v243, v178
	v_max_f32_e32 v206, s9, v206
	v_max_f32_e32 v207, s9, v207
	v_max_f32_e32 v220, s9, v220
	v_max_f32_e32 v221, s9, v221
	v_max_f32_e32 v222, s9, v222
	v_max_f32_e32 v223, s9, v223
	v_max_f32_e32 v242, s9, v242
	v_max_f32_e32 v243, s9, v243
	v_rcp_f32_e32 v206, v206
	v_rcp_f32_e32 v207, v207
	v_rcp_f32_e32 v220, v220
	v_rcp_f32_e32 v221, v221
	v_mul_f32_e32 v222, v206, v222
	v_mul_f32_e32 v223, v207, v223
	v_mul_f32_e32 v242, v220, v242
	v_mul_f32_e32 v243, v221, v243
	v_mul_f32_e32 v18, v222, v18
	v_mul_f32_e32 v19, v223, v19
	v_mul_f32_e32 v20, v242, v20
	v_mul_f32_e32 v21, v243, v21
	v_cvt_f32_ubyte0_e32 v206, v217
	v_cvt_f32_ubyte1_e32 v207, v217
	v_cvt_f32_ubyte2_e32 v220, v217
	v_cvt_f32_ubyte3_e32 v221, v217
	v_cvt_f32_ubyte0_e32 v222, v179
	v_cvt_f32_ubyte1_e32 v223, v179
	v_cvt_f32_ubyte2_e32 v242, v179
	v_cvt_f32_ubyte3_e32 v243, v179
	v_max_f32_e32 v206, s9, v206
	v_max_f32_e32 v207, s9, v207
	v_max_f32_e32 v220, s9, v220
	v_max_f32_e32 v221, s9, v221
	v_max_f32_e32 v222, s9, v222
	v_max_f32_e32 v223, s9, v223
	v_max_f32_e32 v242, s9, v242
	v_max_f32_e32 v243, s9, v243
	v_rcp_f32_e32 v206, v206
	v_rcp_f32_e32 v207, v207
	v_rcp_f32_e32 v220, v220
	v_rcp_f32_e32 v221, v221
	v_mul_f32_e32 v222, v206, v222
	v_mul_f32_e32 v223, v207, v223
	v_mul_f32_e32 v242, v220, v242
	v_mul_f32_e32 v243, v221, v243
	v_mul_f32_e32 v8, v222, v8
	v_mul_f32_e32 v9, v223, v9
	v_mul_f32_e32 v10, v242, v10
	v_mul_f32_e32 v11, v243, v11
	v_cvt_f32_ubyte0_e32 v206, v218
	v_cvt_f32_ubyte1_e32 v207, v218
	v_cvt_f32_ubyte2_e32 v220, v218
	v_cvt_f32_ubyte3_e32 v221, v218
	v_cvt_f32_ubyte0_e32 v222, v180
	v_cvt_f32_ubyte1_e32 v223, v180
	v_cvt_f32_ubyte2_e32 v242, v180
	v_cvt_f32_ubyte3_e32 v243, v180
	v_max_f32_e32 v206, s9, v206
	v_max_f32_e32 v207, s9, v207
	v_max_f32_e32 v220, s9, v220
	v_max_f32_e32 v221, s9, v221
	v_max_f32_e32 v222, s9, v222
	v_max_f32_e32 v223, s9, v223
	v_max_f32_e32 v242, s9, v242
	v_max_f32_e32 v243, s9, v243
	v_rcp_f32_e32 v206, v206
	v_rcp_f32_e32 v207, v207
	v_rcp_f32_e32 v220, v220
	v_rcp_f32_e32 v221, v221
	v_mul_f32_e32 v222, v206, v222
	v_mul_f32_e32 v223, v207, v223
	v_mul_f32_e32 v242, v220, v242
	v_mul_f32_e32 v243, v221, v243
	v_mul_f32_e32 v4, v222, v4
	v_mul_f32_e32 v5, v223, v5
	v_mul_f32_e32 v6, v242, v6
	v_mul_f32_e32 v7, v243, v7
	v_cvt_f32_ubyte0_e32 v206, v219
	v_cvt_f32_ubyte1_e32 v207, v219
	v_cvt_f32_ubyte2_e32 v220, v219
	v_cvt_f32_ubyte3_e32 v221, v219
	v_cvt_f32_ubyte0_e32 v222, v181
	v_cvt_f32_ubyte1_e32 v223, v181
	v_cvt_f32_ubyte2_e32 v242, v181
	v_cvt_f32_ubyte3_e32 v243, v181
	v_max_f32_e32 v206, s9, v206
	v_max_f32_e32 v207, s9, v207
	v_max_f32_e32 v220, s9, v220
	v_max_f32_e32 v221, s9, v221
	v_max_f32_e32 v222, s9, v222
	v_max_f32_e32 v223, s9, v223
	v_max_f32_e32 v242, s9, v242
	v_max_f32_e32 v243, s9, v243
	v_rcp_f32_e32 v206, v206
	v_rcp_f32_e32 v207, v207
	v_rcp_f32_e32 v220, v220
	v_rcp_f32_e32 v221, v221
	v_mul_f32_e32 v222, v206, v222
	v_mul_f32_e32 v223, v207, v223
	v_mul_f32_e32 v242, v220, v242
	v_mul_f32_e32 v243, v221, v243
	v_mul_f32_e32 v0, v222, v0
	v_mul_f32_e32 v1, v223, v1
	v_mul_f32_e32 v2, v242, v2
	v_mul_f32_e32 v3, v243, v3
	s_mov_b32 s68, s66
	s_mov_b32 s41, s64
	s_mov_b32 s67, s44
	s_mov_b32 s40, s46
	s_mov_b64 s[54:55], s[50:51]
	s_mov_b64 s[52:53], s[48:49]
	s_branch .LBB0_233
